# nt hint also on P0 weight loads and the P3 stage-0 fragment loads (read-once, full-line streams)
# speedup vs baseline: 1.0276x; 1.0072x over previous
; template <int MODE>
; DI void conv_item(const float* src, const float* src2, const float* rs, bf16_t* dst, int K, int Nsrc, int nblk, LAS float* scr, int item, int lane) {
;     ...
;   const float* sp = s + (long)(k0 + (lane >> 5)) * Nsrc + col;
; #pragma unroll 8
;   for (int i = 0; i < 32; ++i) {
;     const int kk = 2 * i + (lane >> 5);
;     float w = sp[(long)(2 * i) * Nsrc] * cs;
;     if (rs) w *= rs[k0 + kk];
;     scr[kk * 33 + (lane & 31)] = w;
;   }
.LBB0_34:
	s_lshl_b32 s20, s74, 11
	s_add_i32 s78, s74, 2
	s_add_i32 s88, s74, 4
	v_lshl_add_u64 v[24:25], s[20:21], 2, v[20:21]
	s_lshl_b32 s20, s78, 11
	s_lshl_b32 s62, s73, 11
	s_mov_b32 s63, s21
	s_add_i32 s90, s74, 6
	v_lshl_add_u64 v[28:29], s[20:21], 2, v[20:21]
	s_lshl_b32 s20, s88, 11
	s_add_i32 s79, s73, 2
	s_add_i32 s89, s73, 4
	s_add_i32 s91, s73, 6
	s_add_i32 s92, s74, 8
	s_add_i32 s93, s73, 8
	s_add_i32 s95, s73, 10
	s_add_i32 s97, s73, 12
	s_add_i32 vcc_hi, s73, 14
	v_lshl_add_u64 v[26:27], s[62:63], 2, v[20:21]
	global_load_dword v6, v[24:25], off nt
	global_load_dword v57, v[26:27], off nt
	v_lshl_add_u64 v[24:25], s[20:21], 2, v[20:21]
	s_lshl_b32 s20, s90, 11
	s_mov_b32 s65, s21
	s_mov_b32 s67, s21
	s_mov_b32 s69, s21
	s_mov_b32 s81, s21
	s_add_i32 s94, s74, 10
	s_mov_b32 s83, s21
	s_mov_b32 s85, s21
	s_mov_b32 s87, s21
	s_lshl_b32 s64, s79, 11
	s_lshl_b32 s66, s89, 11
	s_lshl_b32 s68, s91, 11
	s_lshl_b32 s80, s93, 11
	s_lshl_b32 s82, s95, 11
	s_lshl_b32 s84, s97, 11
	s_lshl_b32 s86, vcc_hi, 11
	v_lshl_add_u64 v[26:27], s[20:21], 2, v[20:21]
	s_lshl_b32 s20, s92, 11
	s_add_i32 s96, s74, 12
	v_lshl_add_u64 v[30:31], s[64:65], 2, v[20:21]
	v_lshl_add_u64 v[32:33], s[66:67], 2, v[20:21]
	v_lshl_add_u64 v[34:35], s[68:69], 2, v[20:21]
	v_lshl_add_u64 v[36:37], s[80:81], 2, v[20:21]
	v_lshl_add_u64 v[38:39], s[82:83], 2, v[20:21]
	v_lshl_add_u64 v[58:59], s[84:85], 2, v[20:21]
	v_lshl_add_u64 v[60:61], s[86:87], 2, v[20:21]
	global_load_dword v74, v[28:29], off nt
	global_load_dword v75, v[30:31], off nt
	global_load_dword v76, v[32:33], off nt
	global_load_dword v77, v[34:35], off nt
	global_load_dword v78, v[36:37], off nt
	global_load_dword v79, v[38:39], off nt
	global_load_dword v80, v[58:59], off nt
	global_load_dword v81, v[60:61], off nt
	global_load_dword v82, v[26:27], off nt
	global_load_dword v83, v[24:25], off nt
	v_lshl_add_u64 v[24:25], s[20:21], 2, v[20:21]
	s_lshl_b32 s20, s94, 11
	s_add_i32 vcc_lo, s74, 14
	v_lshl_add_u64 v[26:27], s[20:21], 2, v[20:21]
	s_lshl_b32 s20, s96, 11
	v_lshl_add_u64 v[28:29], s[20:21], 2, v[20:21]
	s_lshl_b32 s20, vcc_lo, 11
	v_lshl_add_u64 v[30:31], s[20:21], 2, v[20:21]
	global_load_dword v84, v[30:31], off nt
	global_load_dword v85, v[28:29], off nt
	global_load_dword v86, v[26:27], off nt
	global_load_dword v87, v[24:25], off nt
	s_lshl_b32 s76, s73, 1
	s_lshl_b32 s77, s74, 1
	v_or_b32_e32 v26, s76, v1
	v_or_b32_e32 v24, s77, v2
	s_add_i32 s74, s74, 16
	s_add_i32 s73, s73, 16
	s_add_i32 s75, s75, -16
	s_lshl_b32 s20, s79, 1
	s_lshl_b32 s64, s78, 1
	s_lshl_b32 s65, s89, 1
	s_lshl_b32 s66, s88, 1
	s_lshl_b32 s67, s91, 1
	s_lshl_b32 s68, s90, 1
	s_lshl_b32 s69, s93, 1
	s_lshl_b32 s76, s92, 1
	s_lshl_b32 s77, s95, 1
	s_lshl_b32 s78, s94, 1
	s_lshl_b32 s79, s97, 1
	s_lshl_b32 s80, s96, 1
	s_lshl_b32 s81, vcc_hi, 1
	s_lshl_b32 s82, vcc_lo, 1
	v_mad_u64_u32 v[24:25], s[62:63], v24, s18, v[4:5]
	v_mad_u64_u32 v[26:27], s[62:63], v26, s18, v[4:5]
	v_or_b32_e32 v25, s20, v1
	v_or_b32_e32 v27, s64, v2
	v_or_b32_e32 v34, s65, v1
	v_or_b32_e32 v32, s66, v2
	v_or_b32_e32 v38, s67, v1
	v_or_b32_e32 v36, s68, v2
	v_or_b32_e32 v60, s69, v1
	v_or_b32_e32 v58, s76, v2
	v_or_b32_e32 v64, s77, v1
	v_or_b32_e32 v62, s78, v2
	v_or_b32_e32 v68, s79, v1
	v_or_b32_e32 v66, s80, v2
	v_or_b32_e32 v72, s81, v1
	v_or_b32_e32 v70, s82, v2
	s_cmp_lg_u32 s75, 0
	v_mad_u64_u32 v[28:29], s[62:63], v27, s18, v[4:5]
	v_mad_u64_u32 v[30:31], s[62:63], v25, s18, v[4:5]
	v_mad_u64_u32 v[32:33], s[62:63], v32, s18, v[4:5]
	v_mad_u64_u32 v[34:35], s[62:63], v34, s18, v[4:5]
	v_mad_u64_u32 v[36:37], s[62:63], v36, s18, v[4:5]
	v_mad_u64_u32 v[38:39], s[62:63], v38, s18, v[4:5]
	v_mad_u64_u32 v[58:59], s[62:63], v58, s18, v[4:5]
	v_mad_u64_u32 v[60:61], s[62:63], v60, s18, v[4:5]
	v_mad_u64_u32 v[62:63], s[62:63], v62, s18, v[4:5]
	v_mad_u64_u32 v[64:65], s[62:63], v64, s18, v[4:5]
	v_mad_u64_u32 v[66:67], s[62:63], v66, s18, v[4:5]
	v_mad_u64_u32 v[68:69], s[62:63], v68, s18, v[4:5]
	v_mad_u64_u32 v[70:71], s[62:63], v70, s18, v[4:5]
	v_mad_u64_u32 v[72:73], s[62:63], v72, s18, v[4:5]
	s_waitcnt vmcnt(15)
	ds_write_b32 v24, v6
	s_waitcnt vmcnt(14)
	ds_write_b32 v26, v57
	s_waitcnt vmcnt(13)
	ds_write_b32 v28, v74
	s_waitcnt vmcnt(12)
	ds_write_b32 v30, v75
	s_waitcnt vmcnt(4)
	ds_write_b32 v32, v83
	ds_write_b32 v34, v76
	ds_write_b32 v36, v82
	ds_write_b32 v38, v77
	s_waitcnt vmcnt(0)
	ds_write_b32 v58, v87
	ds_write_b32 v60, v78
	ds_write_b32 v62, v86
	ds_write_b32 v64, v79
	ds_write_b32 v66, v85
	ds_write_b32 v68, v80
	ds_write_b32 v70, v84
	ds_write_b32 v72, v81
	s_cbranch_scc1 .LBB0_34
; #define LAS __attribute__((address_space(3)))
; DI unsigned pk2(float lo, float hi) { f32x2 v = {lo, hi}; bf16v2 b = __builtin_convertvector(v, bf16v2); return __builtin_bit_cast(unsigned, b); }
; template <int MODE>
; DI void conv_item(const float* src, const float* src2, const float* rs, bf16_t* dst, int K, int Nsrc, int nblk, LAS float* scr, int item, int lane) {
;   const int kb = item / nblk, nb = item % nblk, k0 = 64 * kb, n0 = 32 * nb;
;   const int n = n0 + (lane & 31);
;   int col = n; float cs = 1.f; const float* s = src;
;   if (MODE == 0) {
;     if (n < 1024) { const int head = n >> 7, pp = n & 127, half = (pp >> 4) & 1, jj = pp >> 5, i = pp & 15; col = head * 128 + half * 64 + jj * 16 + i; if (n >= 512) cs = 0.08838834764831845f; }
;     else if (n >= 3072 && n < 4096) { const int c = (n - 3072) & 255, base = n - c; col = base + 64 * ((c >> 5) & 3) + 32 * (c >> 7) + 8 * ((c & 15) >> 2) + 4 * ((c >> 4) & 1) + (c & 3); }
;     else if ((n >= 2048 && n < 3072) || n >= 4608) { const int rho = n & 31; col = (n & ~31) + 8 * ((rho & 15) >> 2) + 4 * (rho >> 4) + (rho & 3); }
;   } else if (MODE == 3) {
;     const int rho = n & 31; col = (n & ~31) + 8 * ((rho & 15) >> 2) + 4 * (rho >> 4) + (rho & 3);
;   } else if (MODE == 1) {
;     const int c = n & 255, r7 = c & 127, rho = r7 & 31; col = (n >> 8) * 128 + (r7 & ~31) + 8 * ((rho & 15) >> 2) + 4 * (rho >> 4) + (rho & 3); if (c >> 7) s = src2;
;   }
;   const float* sp = s + (long)(k0 + (lane >> 5)) * Nsrc + col;
;     ...
;   asm volatile("s_waitcnt lgkmcnt(0)" ::: "memory");
;   const int c = lane & 7;
; #pragma unroll
;   for (int j = 0; j < 4; ++j) {
;     const int nn = (lane >> 3) + 8 * j; const LAS float* q = scr + (8 * c) * 33 + nn;
;     u32x4 o; o.x = pk2(q[0], q[33]); o.y = pk2(q[2 * 33], q[3 * 33]); o.z = pk2(q[4 * 33], q[5 * 33]); o.w = pk2(q[6 * 33], q[7 * 33]);
;     *(u32x4*)(dst + (long)(n0 + nn) * K + k0 + 8 * c) = o;
;   }
;   asm volatile("s_waitcnt lgkmcnt(0)" ::: "memory");
	s_waitcnt lgkmcnt(0)
	v_lshlrev_b32_e32 v6, 1, v23
	ds_read2_b32 v[20:21], v40 offset0:33 offset1:41
	ds_read2_b32 v[28:29], v40 offset1:8
	ds_read2_b32 v[30:31], v40 offset0:66 offset1:74
	ds_read2_b32 v[32:33], v40 offset0:99 offset1:107
	ds_read2_b32 v[34:35], v40 offset0:132 offset1:140
	ds_read2_b32 v[36:37], v40 offset0:165 offset1:173
	ds_read2_b32 v[38:39], v40 offset0:198 offset1:206
	ds_read2_b32 v[58:59], v40 offset0:231 offset1:239
	v_lshl_add_u64 v[60:61], v[10:11], 0, v[6:7]
	v_or_b32_e32 v6, v22, v5
	v_mul_u32_u24_e32 v6, 0xb00, v6
	v_lshlrev_b32_e32 v6, 1, v6
	v_lshl_add_u64 v[62:63], v[60:61], 0, v[6:7]
	v_or_b32_e32 v6, v22, v41
	s_waitcnt lgkmcnt(6)
	v_cvt_pk_bf16_f32 v24, v28, v20
	s_waitcnt lgkmcnt(4)
	v_cvt_pk_bf16_f32 v25, v30, v32
	s_waitcnt lgkmcnt(2)
	v_cvt_pk_bf16_f32 v26, v34, v36
	s_waitcnt lgkmcnt(0)
	v_cvt_pk_bf16_f32 v27, v38, v58
	v_mul_u32_u24_e32 v6, 0xb00, v6
	global_store_dwordx4 v[62:63], v[24:27], off
	v_lshlrev_b32_e32 v6, 1, v6
	v_readlane_b32 s96, v250, 1
	v_cvt_pk_bf16_f32 v24, v29, v21
	v_cvt_pk_bf16_f32 v25, v31, v33
	v_cvt_pk_bf16_f32 v26, v35, v37
	v_cvt_pk_bf16_f32 v27, v39, v59
	v_lshl_add_u64 v[20:21], v[60:61], 0, v[6:7]
	ds_read2_b32 v[28:29], v40 offset0:16 offset1:24
	ds_read2_b32 v[30:31], v40 offset0:49 offset1:57
	ds_read2_b32 v[32:33], v40 offset0:82 offset1:90
	ds_read2_b32 v[34:35], v40 offset0:115 offset1:123
	ds_read2_b32 v[36:37], v40 offset0:148 offset1:156
	ds_read2_b32 v[38:39], v40 offset0:181 offset1:189
	ds_read2_b32 v[58:59], v40 offset0:214 offset1:222
	ds_read2_b32 v[62:63], v40 offset0:247 offset1:255
	v_or_b32_e32 v6, v22, v42
	v_mul_u32_u24_e32 v6, 0xb00, v6
	v_lshlrev_b32_e32 v6, 1, v6
	global_store_dwordx4 v[20:21], v[24:27], off
	v_lshl_add_u64 v[20:21], v[60:61], 0, v[6:7]
	v_or_b32_e32 v6, v22, v43
	v_mul_u32_u24_e32 v6, 0xb00, v6
	s_waitcnt lgkmcnt(6)
	v_cvt_pk_bf16_f32 v24, v28, v30
	s_waitcnt lgkmcnt(4)
	v_cvt_pk_bf16_f32 v25, v32, v34
	s_waitcnt lgkmcnt(2)
	v_cvt_pk_bf16_f32 v26, v36, v38
	s_waitcnt lgkmcnt(0)
	v_cvt_pk_bf16_f32 v27, v58, v62
	v_lshlrev_b32_e32 v6, 1, v6
	global_store_dwordx4 v[20:21], v[24:27], off
	v_lshl_add_u64 v[20:21], v[60:61], 0, v[6:7]
	v_readlane_b32 s94, v250, 3
	v_cvt_pk_bf16_f32 v24, v29, v31
	v_cvt_pk_bf16_f32 v25, v33, v35
	v_cvt_pk_bf16_f32 v26, v37, v39
	v_cvt_pk_bf16_f32 v27, v59, v63
	global_store_dwordx4 v[20:21], v[24:27], off
	s_waitcnt lgkmcnt(0)
	v_readlane_b32 s97, v250, 2
	v_readlane_b32 s95, v250, 4
.LBB0_36:
	s_andn2_saveexec_b64 s[62:63], s[4:5]
	s_cbranch_execz .LBB0_56
	v_add_u16_e32 v6, 0xee00, v139
	v_mul_u32_u24_e32 v20, 0xba2f, v6
	v_lshrrev_b32_e32 v20, 23, v20
	v_mul_lo_u16_e32 v21, 0xb0, v20
	v_sub_u16_e32 v6, v6, v21
	v_lshlrev_b16_e32 v39, 6, v20
	v_lshlrev_b32_e32 v38, 5, v6
	v_lshlrev_b32_e32 v20, 4, v6
	v_and_b32_e32 v6, 4, v6
	v_and_b32_e32 v36, 0xf80, v20
	v_mov_b32_e32 v20, s13
	v_mov_b32_e32 v21, s11
	v_cmp_eq_u32_e32 vcc, 0, v6
	v_mov_b32_e32 v6, s12
	v_and_b32_e32 v37, 0x60, v38
	v_cndmask_b32_e32 v35, v20, v21, vcc
	v_mov_b32_e32 v20, s10
	v_cndmask_b32_e32 v34, v6, v20, vcc
	v_or_b32_e32 v6, v48, v39
	v_lshlrev_b32_e32 v6, 2, v6
	v_lshl_add_u64 v[20:21], s[8:9], 0, v[6:7]
	v_or_b32_e32 v6, v49, v39
	v_lshlrev_b32_e32 v6, 2, v6
	v_lshl_add_u64 v[22:23], s[8:9], 0, v[6:7]
	v_or_b32_e32 v6, v50, v39
	v_lshlrev_b32_e32 v6, 2, v6
	v_lshl_add_u64 v[24:25], s[8:9], 0, v[6:7]
	v_or_b32_e32 v6, v51, v39
	v_lshlrev_b32_e32 v6, 2, v6
	v_lshl_add_u64 v[26:27], s[8:9], 0, v[6:7]
	v_or_b32_e32 v6, v52, v39
	v_lshlrev_b32_e32 v6, 2, v6
	v_lshl_add_u64 v[28:29], s[8:9], 0, v[6:7]
	v_or_b32_e32 v6, v53, v39
	v_lshlrev_b32_e32 v6, 2, v6
	v_or_b32_e32 v57, v2, v39
	v_lshl_add_u64 v[30:31], s[8:9], 0, v[6:7]
	v_or_b32_e32 v6, v54, v39
	v_mul_u32_u24_e32 v58, 0xb00, v57
	v_lshlrev_b32_e32 v6, 2, v6
	v_or3_b32 v36, v55, v36, v37
	v_lshl_add_u64 v[32:33], s[8:9], 0, v[6:7]
	v_lshlrev_b32_e32 v6, 2, v58
	v_lshlrev_b32_e32 v36, 2, v36
	v_mov_b32_e32 v37, v7
	v_lshl_add_u64 v[36:37], v[6:7], 0, v[36:37]
	v_lshl_add_u64 v[34:35], v[34:35], 0, v[36:37]
	s_mov_b64 s[4:5], 0x16000
	v_lshlrev_b32_e32 v6, 2, v57
	v_lshl_add_u64 v[34:35], v[34:35], 0, s[4:5]
	v_lshl_add_u64 v[36:37], s[8:9], 0, v[6:7]
	s_mov_b64 s[64:65], 0
	v_mov_b32_e32 v6, v47
	s_andn2_b64 vcc, exec, s[34:35]
	s_cbranch_vccnz .LBB0_39
; template <int MODE>
; DI void conv_item(const float* src, const float* src2, const float* rs, bf16_t* dst, int K, int Nsrc, int nblk, LAS float* scr, int item, int lane) {
;     ...
;   const float* sp = s + (long)(k0 + (lane >> 5)) * Nsrc + col;
; #pragma unroll 8
;   for (int i = 0; i < 32; ++i) {
;     const int kk = 2 * i + (lane >> 5);
;     float w = sp[(long)(2 * i) * Nsrc] * cs;
;     if (rs) w *= rs[k0 + kk];
;     scr[kk * 33 + (lane & 31)] = w;
;   }
	v_add_co_u32_e32 v120, vcc, 0xfffea000, v34
	s_nop 1
	v_addc_co_u32_e32 v121, vcc, -1, v35, vcc
	s_mov_b64 s[4:5], 0x5800
	global_load_dword v88, v[120:121], off nt
	v_lshl_add_u64 v[120:121], v[120:121], 0, s[4:5]
	global_load_dword v89, v[120:121], off nt
	v_lshl_add_u64 v[120:121], v[120:121], 0, s[4:5]
	global_load_dword v90, v[120:121], off nt
	v_lshl_add_u64 v[120:121], v[120:121], 0, s[4:5]
	global_load_dword v91, v[120:121], off nt
	v_lshl_add_u64 v[120:121], v[120:121], 0, s[4:5]
	global_load_dword v92, v[120:121], off nt
	v_lshl_add_u64 v[120:121], v[120:121], 0, s[4:5]
	global_load_dword v93, v[120:121], off nt
	v_lshl_add_u64 v[120:121], v[120:121], 0, s[4:5]
	global_load_dword v94, v[120:121], off nt
	v_lshl_add_u64 v[120:121], v[120:121], 0, s[4:5]
	global_load_dword v95, v[120:121], off nt
	v_lshl_add_u64 v[120:121], v[120:121], 0, s[4:5]
	global_load_dword v96, v[120:121], off nt
	v_lshl_add_u64 v[120:121], v[120:121], 0, s[4:5]
	global_load_dword v97, v[120:121], off nt
	v_lshl_add_u64 v[120:121], v[120:121], 0, s[4:5]
	global_load_dword v98, v[120:121], off nt
	v_lshl_add_u64 v[120:121], v[120:121], 0, s[4:5]
	global_load_dword v99, v[120:121], off nt
	v_lshl_add_u64 v[120:121], v[120:121], 0, s[4:5]
	global_load_dword v100, v[120:121], off nt
	v_lshl_add_u64 v[120:121], v[120:121], 0, s[4:5]
	global_load_dword v101, v[120:121], off nt
	v_lshl_add_u64 v[120:121], v[120:121], 0, s[4:5]
	global_load_dword v102, v[120:121], off nt
	v_lshl_add_u64 v[120:121], v[120:121], 0, s[4:5]
	global_load_dword v103, v[120:121], off nt
	v_lshl_add_u64 v[120:121], v[120:121], 0, s[4:5]
	global_load_dword v104, v[36:37], off nt
	global_load_dword v105, v[36:37], off offset:8 nt
	global_load_dword v106, v[36:37], off offset:16 nt
	global_load_dword v107, v[36:37], off offset:24 nt
	global_load_dword v108, v[36:37], off offset:32 nt
	global_load_dword v109, v[36:37], off offset:40 nt
	global_load_dword v110, v[36:37], off offset:48 nt
	global_load_dword v111, v[36:37], off offset:56 nt
	global_load_dword v112, v[36:37], off offset:64 nt
	global_load_dword v113, v[36:37], off offset:72 nt
	global_load_dword v114, v[36:37], off offset:80 nt
	global_load_dword v115, v[36:37], off offset:88 nt
	global_load_dword v116, v[36:37], off offset:96 nt
	global_load_dword v117, v[36:37], off offset:104 nt
	global_load_dword v118, v[36:37], off offset:112 nt
	global_load_dword v119, v[36:37], off offset:120 nt
	s_waitcnt vmcnt(15)
	v_mul_f32_e32 v88, v88, v104
	ds_write_b32 v6, v88
	s_waitcnt vmcnt(14)
	v_mul_f32_e32 v89, v89, v105
	ds_write_b32 v6, v89 offset:264
	s_waitcnt vmcnt(13)
	v_mul_f32_e32 v90, v90, v106
	ds_write_b32 v6, v90 offset:528
	s_waitcnt vmcnt(12)
	v_mul_f32_e32 v91, v91, v107
	ds_write_b32 v6, v91 offset:792
	s_waitcnt vmcnt(11)
	v_mul_f32_e32 v92, v92, v108
	ds_write_b32 v6, v92 offset:1056
	s_waitcnt vmcnt(10)
	v_mul_f32_e32 v93, v93, v109
	ds_write_b32 v6, v93 offset:1320
	s_waitcnt vmcnt(9)
	v_mul_f32_e32 v94, v94, v110
	ds_write_b32 v6, v94 offset:1584
	s_waitcnt vmcnt(8)
	v_mul_f32_e32 v95, v95, v111
	ds_write_b32 v6, v95 offset:1848
	s_waitcnt vmcnt(7)
	v_mul_f32_e32 v96, v96, v112
	ds_write_b32 v6, v96 offset:2112
	s_waitcnt vmcnt(6)
	v_mul_f32_e32 v97, v97, v113
	ds_write_b32 v6, v97 offset:2376
	s_waitcnt vmcnt(5)
	v_mul_f32_e32 v98, v98, v114
	ds_write_b32 v6, v98 offset:2640
	s_waitcnt vmcnt(4)
	v_mul_f32_e32 v99, v99, v115
	ds_write_b32 v6, v99 offset:2904
	s_waitcnt vmcnt(3)
	v_mul_f32_e32 v100, v100, v116
	ds_write_b32 v6, v100 offset:3168
	s_waitcnt vmcnt(2)
	v_mul_f32_e32 v101, v101, v117
	ds_write_b32 v6, v101 offset:3432
	s_waitcnt vmcnt(1)
	v_mul_f32_e32 v102, v102, v118
	ds_write_b32 v6, v102 offset:3696
	s_waitcnt vmcnt(0)
; template <int MODE>
; DI void conv_item(const float* src, const float* src2, const float* rs, bf16_t* dst, int K, int Nsrc, int nblk, LAS float* scr, int item, int lane) {
;     ...
;   const float* sp = s + (long)(k0 + (lane >> 5)) * Nsrc + col;
; #pragma unroll 8
;   for (int i = 0; i < 32; ++i) {
;     const int kk = 2 * i + (lane >> 5);
;     float w = sp[(long)(2 * i) * Nsrc] * cs;
;     if (rs) w *= rs[k0 + kk];
;     scr[kk * 33 + (lane & 31)] = w;
;   }
	v_mul_f32_e32 v103, v103, v119
	ds_write_b32 v6, v103 offset:3960
	global_load_dword v88, v[120:121], off nt
	v_lshl_add_u64 v[120:121], v[120:121], 0, s[4:5]
	global_load_dword v89, v[120:121], off nt
	v_lshl_add_u64 v[120:121], v[120:121], 0, s[4:5]
	global_load_dword v90, v[120:121], off nt
	v_lshl_add_u64 v[120:121], v[120:121], 0, s[4:5]
	global_load_dword v91, v[120:121], off nt
	v_lshl_add_u64 v[120:121], v[120:121], 0, s[4:5]
	global_load_dword v92, v[120:121], off nt
	v_lshl_add_u64 v[120:121], v[120:121], 0, s[4:5]
	global_load_dword v93, v[120:121], off nt
	v_lshl_add_u64 v[120:121], v[120:121], 0, s[4:5]
	global_load_dword v94, v[120:121], off nt
	v_lshl_add_u64 v[120:121], v[120:121], 0, s[4:5]
	global_load_dword v95, v[120:121], off nt
	v_lshl_add_u64 v[120:121], v[120:121], 0, s[4:5]
	global_load_dword v96, v[120:121], off nt
	v_lshl_add_u64 v[120:121], v[120:121], 0, s[4:5]
	global_load_dword v97, v[120:121], off nt
	v_lshl_add_u64 v[120:121], v[120:121], 0, s[4:5]
	global_load_dword v98, v[120:121], off nt
	v_lshl_add_u64 v[120:121], v[120:121], 0, s[4:5]
	global_load_dword v99, v[120:121], off nt
	v_lshl_add_u64 v[120:121], v[120:121], 0, s[4:5]
	global_load_dword v100, v[120:121], off nt
	v_lshl_add_u64 v[120:121], v[120:121], 0, s[4:5]
	global_load_dword v101, v[120:121], off nt
	v_lshl_add_u64 v[120:121], v[120:121], 0, s[4:5]
	global_load_dword v102, v[120:121], off nt
	v_lshl_add_u64 v[120:121], v[120:121], 0, s[4:5]
	global_load_dword v103, v[120:121], off nt
	v_lshl_add_u64 v[120:121], v[120:121], 0, s[4:5]
	global_load_dword v104, v[36:37], off offset:128 nt
	global_load_dword v105, v[36:37], off offset:136 nt
	global_load_dword v106, v[36:37], off offset:144 nt
	global_load_dword v107, v[36:37], off offset:152 nt
	global_load_dword v108, v[36:37], off offset:160 nt
	global_load_dword v109, v[36:37], off offset:168 nt
	global_load_dword v110, v[36:37], off offset:176 nt
	global_load_dword v111, v[36:37], off offset:184 nt
	global_load_dword v112, v[36:37], off offset:192 nt
	global_load_dword v113, v[36:37], off offset:200 nt
	global_load_dword v114, v[36:37], off offset:208 nt
	global_load_dword v115, v[36:37], off offset:216 nt
	global_load_dword v116, v[36:37], off offset:224 nt
	global_load_dword v117, v[36:37], off offset:232 nt
	global_load_dword v118, v[36:37], off offset:240 nt
	global_load_dword v119, v[36:37], off offset:248 nt
	s_waitcnt vmcnt(15)
	v_mul_f32_e32 v88, v88, v104
	ds_write_b32 v6, v88 offset:4224
	s_waitcnt vmcnt(14)
	v_mul_f32_e32 v89, v89, v105
	ds_write_b32 v6, v89 offset:4488
	s_waitcnt vmcnt(13)
	v_mul_f32_e32 v90, v90, v106
	ds_write_b32 v6, v90 offset:4752
	s_waitcnt vmcnt(12)
	v_mul_f32_e32 v91, v91, v107
	ds_write_b32 v6, v91 offset:5016
	s_waitcnt vmcnt(11)
	v_mul_f32_e32 v92, v92, v108
	ds_write_b32 v6, v92 offset:5280
	s_waitcnt vmcnt(10)
	v_mul_f32_e32 v93, v93, v109
	ds_write_b32 v6, v93 offset:5544
	s_waitcnt vmcnt(9)
	v_mul_f32_e32 v94, v94, v110
	ds_write_b32 v6, v94 offset:5808
	s_waitcnt vmcnt(8)
	v_mul_f32_e32 v95, v95, v111
	ds_write_b32 v6, v95 offset:6072
	s_waitcnt vmcnt(7)
	v_mul_f32_e32 v96, v96, v112
	ds_write_b32 v6, v96 offset:6336
	s_waitcnt vmcnt(6)
	v_mul_f32_e32 v97, v97, v113
	ds_write_b32 v6, v97 offset:6600
	s_waitcnt vmcnt(5)
	v_mul_f32_e32 v98, v98, v114
	ds_write_b32 v6, v98 offset:6864
	s_waitcnt vmcnt(4)
	v_mul_f32_e32 v99, v99, v115
	ds_write_b32 v6, v99 offset:7128
	s_waitcnt vmcnt(3)
	v_mul_f32_e32 v100, v100, v116
	ds_write_b32 v6, v100 offset:7392
	s_waitcnt vmcnt(2)
	v_mul_f32_e32 v101, v101, v117
	ds_write_b32 v6, v101 offset:7656
	s_waitcnt vmcnt(1)
	v_mul_f32_e32 v102, v102, v118
	ds_write_b32 v6, v102 offset:7920
	s_waitcnt vmcnt(0)
	v_mul_f32_e32 v103, v103, v119
	ds_write_b32 v6, v103 offset:8184
	s_branch .LBB0_55

; template <int MODE>
; DI void conv_item(const float* src, const float* src2, const float* rs, bf16_t* dst, int K, int Nsrc, int nblk, LAS float* scr, int item, int lane) {
;     ...
;   for (int i = 0; i < 32; ++i) {
;     const int kk = 2 * i + (lane >> 5);
;     float w = sp[(long)(2 * i) * Nsrc] * cs;
;     if (rs) w *= rs[k0 + kk];
;     scr[kk * 33 + (lane & 31)] = w;
;   }
.LBB0_39:
	v_add_co_u32_e32 v58, vcc, 0xfffea000, v34
	s_nop 1
	v_addc_co_u32_e32 v59, vcc, -1, v35, vcc
	global_load_dword v57, v[58:59], off nt
	v_cndmask_b32_e64 v58, 0, 1, s[34:35]
	v_cmp_ne_u32_e64 s[4:5], 1, v58
	s_andn2_b64 vcc, exec, s[34:35]
	s_cbranch_vccnz .LBB0_41
	v_lshl_add_u64 v[58:59], v[36:37], 0, s[64:65]
	global_load_dword v58, v[58:59], off nt
	s_waitcnt vmcnt(0)
	v_mul_f32_e32 v57, v57, v58
.LBB0_41:
	v_add_co_u32_e32 v58, vcc, 0xffff0000, v34
	s_waitcnt vmcnt(0)
	ds_write_b32 v6, v57
	v_addc_co_u32_e32 v59, vcc, -1, v35, vcc
	global_load_dword v58, v[58:59], off offset:-2048 nt
	s_and_b64 vcc, exec, s[4:5]
	s_cbranch_vccnz .LBB0_43
	v_lshl_add_u64 v[60:61], v[32:33], 0, s[64:65]
	global_load_dword v57, v[60:61], off nt
	s_waitcnt vmcnt(0)
	v_mul_f32_e32 v58, v58, v57
.LBB0_43:
	v_add_co_u32_e32 v60, vcc, 0xffff5000, v34
	s_waitcnt vmcnt(0)
	ds_write_b32 v6, v58 offset:264
	v_addc_co_u32_e32 v61, vcc, -1, v35, vcc
	global_load_dword v57, v[60:61], off nt
	s_and_b64 vcc, exec, s[4:5]
	s_cbranch_vccnz .LBB0_45
	v_lshl_add_u64 v[58:59], v[30:31], 0, s[64:65]
	global_load_dword v58, v[58:59], off nt
	s_waitcnt vmcnt(0)
	v_mul_f32_e32 v57, v57, v58
.LBB0_45:
	v_add_co_u32_e32 v58, vcc, 0xffffb000, v34
	s_waitcnt vmcnt(0)
	ds_write_b32 v6, v57 offset:528
	v_addc_co_u32_e32 v59, vcc, -1, v35, vcc
	global_load_dword v58, v[58:59], off offset:-2048 nt
	s_and_b64 vcc, exec, s[4:5]
	s_cbranch_vccnz .LBB0_47
	v_lshl_add_u64 v[60:61], v[28:29], 0, s[64:65]
	global_load_dword v57, v[60:61], off nt
	s_waitcnt vmcnt(0)
	v_mul_f32_e32 v58, v58, v57
.LBB0_47:
	global_load_dword v57, v[34:35], off nt
	s_and_b64 vcc, exec, s[4:5]
	s_waitcnt vmcnt(1)
	ds_write_b32 v6, v58 offset:792
	s_cbranch_vccnz .LBB0_49
	v_lshl_add_u64 v[58:59], v[26:27], 0, s[64:65]
	global_load_dword v58, v[58:59], off nt
	s_waitcnt vmcnt(0)
	v_mul_f32_e32 v57, v57, v58
.LBB0_49:
	v_add_co_u32_e32 v58, vcc, 0x5000, v34
	s_waitcnt vmcnt(0)
	ds_write_b32 v6, v57 offset:1056
	v_addc_co_u32_e32 v59, vcc, 0, v35, vcc
	global_load_dword v58, v[58:59], off offset:2048 nt
	s_and_b64 vcc, exec, s[4:5]
	s_cbranch_vccnz .LBB0_51
	v_lshl_add_u64 v[60:61], v[24:25], 0, s[64:65]
	global_load_dword v57, v[60:61], off nt
	s_waitcnt vmcnt(0)
	v_mul_f32_e32 v58, v58, v57
.LBB0_51:
	v_add_co_u32_e32 v60, vcc, 0xb000, v34
	s_waitcnt vmcnt(0)
	ds_write_b32 v6, v58 offset:1320
	v_addc_co_u32_e32 v61, vcc, 0, v35, vcc
	global_load_dword v57, v[60:61], off nt
	s_and_b64 vcc, exec, s[4:5]
	s_cbranch_vccnz .LBB0_53
	v_lshl_add_u64 v[58:59], v[22:23], 0, s[64:65]
	global_load_dword v58, v[58:59], off nt
	s_waitcnt vmcnt(0)
	v_mul_f32_e32 v57, v57, v58
.LBB0_53:
	v_add_co_u32_e32 v58, vcc, 0x10000, v34
	s_waitcnt vmcnt(0)
	ds_write_b32 v6, v57 offset:1584
	v_addc_co_u32_e32 v59, vcc, 0, v35, vcc
	global_load_dword v58, v[58:59], off offset:2048 nt
	s_and_b64 vcc, exec, s[4:5]
	s_cbranch_vccnz .LBB0_38
	v_lshl_add_u64 v[60:61], v[20:21], 0, s[64:65]
	global_load_dword v57, v[60:61], off nt
	s_waitcnt vmcnt(0)
	v_mul_f32_e32 v58, v58, v57
	s_branch .LBB0_38

; #define LAS __attribute__((address_space(3)))
; DI unsigned pk2(float lo, float hi) { f32x2 v = {lo, hi}; bf16v2 b = __builtin_convertvector(v, bf16v2); return __builtin_bit_cast(unsigned, b); }
; template <int MODE>
; DI void conv_item(const float* src, const float* src2, const float* rs, bf16_t* dst, int K, int Nsrc, int nblk, LAS float* scr, int item, int lane) {
;     ...
;   const float* sp = s + (long)(k0 + (lane >> 5)) * Nsrc + col;
; #pragma unroll 8
;   for (int i = 0; i < 32; ++i) {
;     const int kk = 2 * i + (lane >> 5);
;     float w = sp[(long)(2 * i) * Nsrc] * cs;
;     if (rs) w *= rs[k0 + kk];
;     scr[kk * 33 + (lane & 31)] = w;
;   }
;   asm volatile("s_waitcnt lgkmcnt(0)" ::: "memory");
;   const int c = lane & 7;
; #pragma unroll
;   for (int j = 0; j < 4; ++j) {
;     const int nn = (lane >> 3) + 8 * j; const LAS float* q = scr + (8 * c) * 33 + nn;
;     u32x4 o; o.x = pk2(q[0], q[33]); o.y = pk2(q[2 * 33], q[3 * 33]); o.z = pk2(q[4 * 33], q[5 * 33]); o.w = pk2(q[6 * 33], q[7 * 33]);
;     *(u32x4*)(dst + (long)(n0 + nn) * K + k0 + 8 * c) = o;
;   }
.LBB0_59:
	s_lshl_b32 s20, s69, 11
	s_add_i32 s76, s69, 2
	s_add_i32 s86, s69, 4
	v_lshl_add_u64 v[24:25], s[20:21], 2, v[20:21]
	s_lshl_b32 s20, s76, 11
	s_lshl_b32 s60, s68, 11
	s_mov_b32 s61, s21
	s_add_i32 s88, s69, 6
	v_lshl_add_u64 v[28:29], s[20:21], 2, v[20:21]
	s_lshl_b32 s20, s86, 11
	s_add_i32 s77, s68, 2
	s_add_i32 s87, s68, 4
	s_add_i32 s89, s68, 6
	s_add_i32 s90, s69, 8
	s_add_i32 s91, s68, 8
	s_add_i32 s93, s68, 10
	s_add_i32 s95, s68, 12
	s_add_i32 s97, s68, 14
	v_lshl_add_u64 v[26:27], s[60:61], 2, v[20:21]
	global_load_dword v6, v[24:25], off nt
	global_load_dword v57, v[26:27], off nt
	v_lshl_add_u64 v[24:25], s[20:21], 2, v[20:21]
	s_lshl_b32 s20, s88, 11
	s_mov_b32 s63, s21
	s_mov_b32 s65, s21
	s_mov_b32 s67, s21
	s_mov_b32 s79, s21
	s_add_i32 s92, s69, 10
	s_mov_b32 s81, s21
	s_mov_b32 s83, s21
	s_mov_b32 s85, s21
	s_lshl_b32 s62, s77, 11
	s_lshl_b32 s64, s87, 11
	s_lshl_b32 s66, s89, 11
	s_lshl_b32 s78, s91, 11
	s_lshl_b32 s80, s93, 11
	s_lshl_b32 s82, s95, 11
	s_lshl_b32 s84, s97, 11
	v_lshl_add_u64 v[26:27], s[20:21], 2, v[20:21]
	s_lshl_b32 s20, s90, 11
	s_add_i32 s94, s69, 12
	v_lshl_add_u64 v[30:31], s[62:63], 2, v[20:21]
	v_lshl_add_u64 v[32:33], s[64:65], 2, v[20:21]
	v_lshl_add_u64 v[34:35], s[66:67], 2, v[20:21]
	v_lshl_add_u64 v[36:37], s[78:79], 2, v[20:21]
	v_lshl_add_u64 v[38:39], s[80:81], 2, v[20:21]
	v_lshl_add_u64 v[58:59], s[82:83], 2, v[20:21]
	v_lshl_add_u64 v[60:61], s[84:85], 2, v[20:21]
	global_load_dword v74, v[28:29], off nt
	global_load_dword v75, v[30:31], off nt
	global_load_dword v76, v[32:33], off nt
	global_load_dword v77, v[34:35], off nt
	global_load_dword v78, v[36:37], off nt
	global_load_dword v79, v[38:39], off nt
	global_load_dword v80, v[58:59], off nt
	global_load_dword v81, v[60:61], off nt
	global_load_dword v82, v[26:27], off nt
	global_load_dword v83, v[24:25], off nt
	v_lshl_add_u64 v[24:25], s[20:21], 2, v[20:21]
	s_lshl_b32 s20, s92, 11
	s_add_i32 s96, s69, 14
	v_lshl_add_u64 v[26:27], s[20:21], 2, v[20:21]
	s_lshl_b32 s20, s94, 11
	v_lshl_add_u64 v[28:29], s[20:21], 2, v[20:21]
	s_lshl_b32 s20, s96, 11
	v_lshl_add_u64 v[30:31], s[20:21], 2, v[20:21]
	global_load_dword v84, v[30:31], off nt
	global_load_dword v85, v[28:29], off nt
	global_load_dword v86, v[26:27], off nt
	global_load_dword v87, v[24:25], off nt
	s_lshl_b32 s74, s68, 1
	s_lshl_b32 s75, s69, 1
	v_or_b32_e32 v26, s74, v1
	v_or_b32_e32 v24, s75, v2
	s_add_i32 s69, s69, 16
	s_add_i32 s68, s68, 16
	s_add_i32 s73, s73, -16
	s_lshl_b32 s20, s77, 1
	s_lshl_b32 s62, s76, 1
	s_lshl_b32 s63, s87, 1
	s_lshl_b32 s64, s86, 1
	s_lshl_b32 s65, s89, 1
	s_lshl_b32 s66, s88, 1
	s_lshl_b32 s67, s91, 1
	s_lshl_b32 s74, s90, 1
	s_lshl_b32 s75, s93, 1
	s_lshl_b32 s76, s92, 1
	s_lshl_b32 s77, s95, 1
	s_lshl_b32 s78, s94, 1
	s_lshl_b32 s79, s97, 1
	s_lshl_b32 s80, s96, 1
	v_mad_u64_u32 v[24:25], s[60:61], v24, s18, v[4:5]
	v_mad_u64_u32 v[26:27], s[60:61], v26, s18, v[4:5]
	v_or_b32_e32 v25, s20, v1
	v_or_b32_e32 v27, s62, v2
	v_or_b32_e32 v34, s63, v1
	v_or_b32_e32 v32, s64, v2
	v_or_b32_e32 v38, s65, v1
	v_or_b32_e32 v36, s66, v2
	v_or_b32_e32 v60, s67, v1
	v_or_b32_e32 v58, s74, v2
	v_or_b32_e32 v64, s75, v1
	v_or_b32_e32 v62, s76, v2
	v_or_b32_e32 v68, s77, v1
	v_or_b32_e32 v66, s78, v2
	v_or_b32_e32 v72, s79, v1
	v_or_b32_e32 v70, s80, v2
	s_cmp_lg_u32 s73, 0
	v_mad_u64_u32 v[28:29], s[60:61], v27, s18, v[4:5]
	v_mad_u64_u32 v[30:31], s[60:61], v25, s18, v[4:5]
	v_mad_u64_u32 v[32:33], s[60:61], v32, s18, v[4:5]
	v_mad_u64_u32 v[34:35], s[60:61], v34, s18, v[4:5]
	v_mad_u64_u32 v[36:37], s[60:61], v36, s18, v[4:5]
	v_mad_u64_u32 v[38:39], s[60:61], v38, s18, v[4:5]
	v_mad_u64_u32 v[58:59], s[60:61], v58, s18, v[4:5]
	v_mad_u64_u32 v[60:61], s[60:61], v60, s18, v[4:5]
	v_mad_u64_u32 v[62:63], s[60:61], v62, s18, v[4:5]
	v_mad_u64_u32 v[64:65], s[60:61], v64, s18, v[4:5]
	v_mad_u64_u32 v[66:67], s[60:61], v66, s18, v[4:5]
	v_mad_u64_u32 v[68:69], s[60:61], v68, s18, v[4:5]
	v_mad_u64_u32 v[70:71], s[60:61], v70, s18, v[4:5]
	v_mad_u64_u32 v[72:73], s[60:61], v72, s18, v[4:5]
	s_waitcnt vmcnt(15)
	ds_write_b32 v24, v6
	s_waitcnt vmcnt(14)
	ds_write_b32 v26, v57
	s_waitcnt vmcnt(13)
	ds_write_b32 v28, v74
	s_waitcnt vmcnt(12)
	ds_write_b32 v30, v75
	s_waitcnt vmcnt(4)
	ds_write_b32 v32, v83
	ds_write_b32 v34, v76
	ds_write_b32 v36, v82
	ds_write_b32 v38, v77
	s_waitcnt vmcnt(0)
	ds_write_b32 v58, v87
	ds_write_b32 v60, v78
	ds_write_b32 v62, v86
	ds_write_b32 v64, v79
	ds_write_b32 v66, v85
	ds_write_b32 v68, v80
	ds_write_b32 v70, v84
	ds_write_b32 v72, v81
	s_cbranch_scc1 .LBB0_59
	s_waitcnt lgkmcnt(0)
	ds_read2_b32 v[20:21], v40 offset0:33 offset1:41
	ds_read2_b32 v[28:29], v40 offset1:8
	ds_read2_b32 v[30:31], v40 offset0:66 offset1:74
	ds_read2_b32 v[32:33], v40 offset0:99 offset1:107
	ds_read2_b32 v[34:35], v40 offset0:132 offset1:140
	ds_read2_b32 v[36:37], v40 offset0:165 offset1:173
	ds_read2_b32 v[38:39], v40 offset0:198 offset1:206
	ds_read2_b32 v[58:59], v40 offset0:231 offset1:239
	v_lshlrev_b32_e32 v6, 1, v23
	v_lshl_add_u64 v[60:61], v[14:15], 0, v[6:7]
	v_or_b32_e32 v6, v22, v5
	v_lshlrev_b32_e32 v6, 11, v6
	s_waitcnt lgkmcnt(6)
	v_cvt_pk_bf16_f32 v24, v28, v20
	s_waitcnt lgkmcnt(4)
	v_cvt_pk_bf16_f32 v25, v30, v32
	s_waitcnt lgkmcnt(2)
	v_cvt_pk_bf16_f32 v26, v34, v36
	s_waitcnt lgkmcnt(0)
	v_cvt_pk_bf16_f32 v27, v38, v58
	v_lshl_add_u64 v[62:63], v[60:61], 0, v[6:7]
	global_store_dwordx4 v[62:63], v[24:27], off
	v_or_b32_e32 v6, v22, v41
	v_lshlrev_b32_e32 v6, 11, v6
	v_cvt_pk_bf16_f32 v24, v29, v21
	v_cvt_pk_bf16_f32 v25, v31, v33
	v_cvt_pk_bf16_f32 v26, v35, v37
	v_cvt_pk_bf16_f32 v27, v39, v59
	ds_read2_b32 v[28:29], v40 offset0:49 offset1:57
	ds_read2_b32 v[30:31], v40 offset0:16 offset1:24
	ds_read2_b32 v[32:33], v40 offset0:82 offset1:90
	ds_read2_b32 v[34:35], v40 offset0:115 offset1:123
	ds_read2_b32 v[36:37], v40 offset0:148 offset1:156
	ds_read2_b32 v[38:39], v40 offset0:181 offset1:189
	ds_read2_b32 v[58:59], v40 offset0:214 offset1:222
	ds_read2_b32 v[62:63], v40 offset0:247 offset1:255
	v_lshl_add_u64 v[20:21], v[60:61], 0, v[6:7]
	v_or_b32_e32 v6, v22, v42
	v_lshlrev_b32_e32 v6, 11, v6
	global_store_dwordx4 v[20:21], v[24:27], off
	v_lshl_add_u64 v[20:21], v[60:61], 0, v[6:7]
	v_or_b32_e32 v6, v22, v43
	s_waitcnt lgkmcnt(6)
	v_cvt_pk_bf16_f32 v24, v30, v28
	s_waitcnt lgkmcnt(4)
	v_cvt_pk_bf16_f32 v25, v32, v34
	s_waitcnt lgkmcnt(2)
	v_cvt_pk_bf16_f32 v26, v36, v38
	s_waitcnt lgkmcnt(0)
	v_cvt_pk_bf16_f32 v27, v58, v62
	v_lshlrev_b32_e32 v6, 11, v6
	global_store_dwordx4 v[20:21], v[24:27], off
	v_lshl_add_u64 v[20:21], v[60:61], 0, v[6:7]
	v_readlane_b32 s96, v250, 1
	v_cvt_pk_bf16_f32 v24, v31, v29
	v_cvt_pk_bf16_f32 v25, v33, v35
	v_cvt_pk_bf16_f32 v26, v37, v39
	v_cvt_pk_bf16_f32 v27, v59, v63
	global_store_dwordx4 v[20:21], v[24:27], off
	s_waitcnt lgkmcnt(0)
	v_readlane_b32 s94, v250, 3
	v_readlane_b32 s97, v250, 2
	v_readlane_b32 s95, v250, 4

; #define LAS __attribute__((address_space(3)))
; DI unsigned pk2(float lo, float hi) { f32x2 v = {lo, hi}; bf16v2 b = __builtin_convertvector(v, bf16v2); return __builtin_bit_cast(unsigned, b); }
; template <int MODE>
; DI void conv_item(const float* src, const float* src2, const float* rs, bf16_t* dst, int K, int Nsrc, int nblk, LAS float* scr, int item, int lane) {
;     ...
;   const float* sp = s + (long)(k0 + (lane >> 5)) * Nsrc + col;
; #pragma unroll 8
;   for (int i = 0; i < 32; ++i) {
;     const int kk = 2 * i + (lane >> 5);
;     float w = sp[(long)(2 * i) * Nsrc] * cs;
;     if (rs) w *= rs[k0 + kk];
;     scr[kk * 33 + (lane & 31)] = w;
;   }
;   asm volatile("s_waitcnt lgkmcnt(0)" ::: "memory");
;   const int c = lane & 7;
; #pragma unroll
;   for (int j = 0; j < 4; ++j) {
;     const int nn = (lane >> 3) + 8 * j; const LAS float* q = scr + (8 * c) * 33 + nn;
;     u32x4 o; o.x = pk2(q[0], q[33]); o.y = pk2(q[2 * 33], q[3 * 33]); o.z = pk2(q[4 * 33], q[5 * 33]); o.w = pk2(q[6 * 33], q[7 * 33]);
;     *(u32x4*)(dst + (long)(n0 + nn) * K + k0 + 8 * c) = o;
;   }
.LBB0_64:
	s_lshl_b32 s20, s67, 11
	s_add_i32 s74, s67, 2
	s_add_i32 s84, s67, 4
	v_lshl_add_u64 v[24:25], s[20:21], 2, v[20:21]
	s_lshl_b32 s20, s74, 11
	s_lshl_b32 s58, s66, 11
	s_mov_b32 s59, s21
	s_add_i32 s86, s67, 6
	v_lshl_add_u64 v[28:29], s[20:21], 2, v[20:21]
	s_lshl_b32 s20, s84, 11
	s_add_i32 s75, s66, 2
	s_add_i32 s85, s66, 4
	s_add_i32 s87, s66, 6
	s_add_i32 s88, s67, 8
	s_add_i32 s89, s66, 8
	s_add_i32 s91, s66, 10
	s_add_i32 s93, s66, 12
	s_add_i32 s95, s66, 14
	v_lshl_add_u64 v[26:27], s[58:59], 2, v[20:21]
	global_load_dword v6, v[24:25], off nt
	global_load_dword v57, v[26:27], off nt
	v_lshl_add_u64 v[24:25], s[20:21], 2, v[20:21]
	s_lshl_b32 s20, s86, 11
	s_mov_b32 s61, s21
	s_mov_b32 s63, s21
	s_mov_b32 s65, s21
	s_mov_b32 s77, s21
	s_add_i32 s90, s67, 10
	s_mov_b32 s79, s21
	s_mov_b32 s81, s21
	s_mov_b32 s83, s21
	s_lshl_b32 s60, s75, 11
	s_lshl_b32 s62, s85, 11
	s_lshl_b32 s64, s87, 11
	s_lshl_b32 s76, s89, 11
	s_lshl_b32 s78, s91, 11
	s_lshl_b32 s80, s93, 11
	s_lshl_b32 s82, s95, 11
	v_lshl_add_u64 v[26:27], s[20:21], 2, v[20:21]
	s_lshl_b32 s20, s88, 11
	s_add_i32 s92, s67, 12
	v_lshl_add_u64 v[30:31], s[60:61], 2, v[20:21]
	v_lshl_add_u64 v[32:33], s[62:63], 2, v[20:21]
	v_lshl_add_u64 v[34:35], s[64:65], 2, v[20:21]
	v_lshl_add_u64 v[36:37], s[76:77], 2, v[20:21]
	v_lshl_add_u64 v[38:39], s[78:79], 2, v[20:21]
	v_lshl_add_u64 v[58:59], s[80:81], 2, v[20:21]
	v_lshl_add_u64 v[60:61], s[82:83], 2, v[20:21]
	global_load_dword v74, v[28:29], off nt
	global_load_dword v75, v[30:31], off nt
	global_load_dword v76, v[32:33], off nt
	global_load_dword v77, v[34:35], off nt
	global_load_dword v78, v[36:37], off nt
	global_load_dword v79, v[38:39], off nt
	global_load_dword v80, v[58:59], off nt
	global_load_dword v81, v[60:61], off nt
	global_load_dword v82, v[26:27], off nt
	global_load_dword v83, v[24:25], off nt
	v_lshl_add_u64 v[24:25], s[20:21], 2, v[20:21]
	s_lshl_b32 s20, s90, 11
	s_add_i32 s94, s67, 14
	v_lshl_add_u64 v[26:27], s[20:21], 2, v[20:21]
	s_lshl_b32 s20, s92, 11
	v_lshl_add_u64 v[28:29], s[20:21], 2, v[20:21]
	s_lshl_b32 s20, s94, 11
	v_lshl_add_u64 v[30:31], s[20:21], 2, v[20:21]
	global_load_dword v84, v[30:31], off nt
	global_load_dword v85, v[28:29], off nt
	global_load_dword v86, v[26:27], off nt
	global_load_dword v87, v[24:25], off nt
	s_lshl_b32 s69, s66, 1
	s_lshl_b32 s73, s67, 1
	v_or_b32_e32 v26, s69, v1
	v_or_b32_e32 v24, s73, v2
	s_add_i32 s67, s67, 16
	s_add_i32 s66, s66, 16
	s_add_i32 s68, s68, -16
	s_lshl_b32 s20, s75, 1
	s_lshl_b32 s60, s74, 1
	s_lshl_b32 s61, s85, 1
	s_lshl_b32 s62, s84, 1
	s_lshl_b32 s63, s87, 1
	s_lshl_b32 s64, s86, 1
	s_lshl_b32 s65, s89, 1
	s_lshl_b32 s69, s88, 1
	s_lshl_b32 s73, s91, 1
	s_lshl_b32 s74, s90, 1
	s_lshl_b32 s75, s93, 1
	s_lshl_b32 s76, s92, 1
	s_lshl_b32 s77, s95, 1
	s_lshl_b32 s78, s94, 1
	v_mad_u64_u32 v[24:25], s[58:59], v24, s18, v[4:5]
	v_mad_u64_u32 v[26:27], s[58:59], v26, s18, v[4:5]
	v_or_b32_e32 v25, s20, v1
	v_or_b32_e32 v27, s60, v2
	v_or_b32_e32 v34, s61, v1
	v_or_b32_e32 v32, s62, v2
	v_or_b32_e32 v38, s63, v1
	v_or_b32_e32 v36, s64, v2
	v_or_b32_e32 v60, s65, v1
	v_or_b32_e32 v58, s69, v2
	v_or_b32_e32 v64, s73, v1
	v_or_b32_e32 v62, s74, v2
	v_or_b32_e32 v68, s75, v1
	v_or_b32_e32 v66, s76, v2
	v_or_b32_e32 v72, s77, v1
	v_or_b32_e32 v70, s78, v2
	s_cmp_lg_u32 s68, 0
	v_mad_u64_u32 v[28:29], s[58:59], v27, s18, v[4:5]
	v_mad_u64_u32 v[30:31], s[58:59], v25, s18, v[4:5]
	v_mad_u64_u32 v[32:33], s[58:59], v32, s18, v[4:5]
	v_mad_u64_u32 v[34:35], s[58:59], v34, s18, v[4:5]
	v_mad_u64_u32 v[36:37], s[58:59], v36, s18, v[4:5]
	v_mad_u64_u32 v[38:39], s[58:59], v38, s18, v[4:5]
	v_mad_u64_u32 v[58:59], s[58:59], v58, s18, v[4:5]
	v_mad_u64_u32 v[60:61], s[58:59], v60, s18, v[4:5]
	v_mad_u64_u32 v[62:63], s[58:59], v62, s18, v[4:5]
	v_mad_u64_u32 v[64:65], s[58:59], v64, s18, v[4:5]
	v_mad_u64_u32 v[66:67], s[58:59], v66, s18, v[4:5]
	v_mad_u64_u32 v[68:69], s[58:59], v68, s18, v[4:5]
	v_mad_u64_u32 v[70:71], s[58:59], v70, s18, v[4:5]
	v_mad_u64_u32 v[72:73], s[58:59], v72, s18, v[4:5]
	s_waitcnt vmcnt(15)
	ds_write_b32 v24, v6
	s_waitcnt vmcnt(14)
	ds_write_b32 v26, v57
	s_waitcnt vmcnt(13)
	ds_write_b32 v28, v74
	s_waitcnt vmcnt(12)
	ds_write_b32 v30, v75
	s_waitcnt vmcnt(4)
	ds_write_b32 v32, v83
	ds_write_b32 v34, v76
	ds_write_b32 v36, v82
	ds_write_b32 v38, v77
	s_waitcnt vmcnt(0)
	ds_write_b32 v58, v87
	ds_write_b32 v60, v78
	ds_write_b32 v62, v86
	ds_write_b32 v64, v79
	ds_write_b32 v66, v85
	ds_write_b32 v68, v80
	ds_write_b32 v70, v84
	ds_write_b32 v72, v81
	s_cbranch_scc1 .LBB0_64
	s_waitcnt lgkmcnt(0)
	ds_read2_b32 v[20:21], v40 offset0:33 offset1:41
	ds_read2_b32 v[28:29], v40 offset1:8
	ds_read2_b32 v[30:31], v40 offset0:66 offset1:74
	ds_read2_b32 v[32:33], v40 offset0:99 offset1:107
	ds_read2_b32 v[34:35], v40 offset0:132 offset1:140
	ds_read2_b32 v[36:37], v40 offset0:165 offset1:173
	ds_read2_b32 v[38:39], v40 offset0:198 offset1:206
	ds_read2_b32 v[58:59], v40 offset0:231 offset1:239
	v_lshlrev_b32_e32 v6, 1, v23
	v_lshl_add_u64 v[60:61], v[16:17], 0, v[6:7]
	v_or_b32_e32 v6, v22, v5
	v_lshlrev_b32_e32 v6, 10, v6
	s_waitcnt lgkmcnt(6)
	v_cvt_pk_bf16_f32 v24, v28, v20
	s_waitcnt lgkmcnt(4)
	v_cvt_pk_bf16_f32 v25, v30, v32
	s_waitcnt lgkmcnt(2)
	v_cvt_pk_bf16_f32 v26, v34, v36
	s_waitcnt lgkmcnt(0)
	v_cvt_pk_bf16_f32 v27, v38, v58
	v_lshl_add_u64 v[62:63], v[60:61], 0, v[6:7]
	global_store_dwordx4 v[62:63], v[24:27], off
	v_or_b32_e32 v6, v22, v41
	v_lshlrev_b32_e32 v6, 10, v6
	v_cvt_pk_bf16_f32 v24, v29, v21
	v_cvt_pk_bf16_f32 v25, v31, v33
	v_cvt_pk_bf16_f32 v26, v35, v37
	v_cvt_pk_bf16_f32 v27, v39, v59
	ds_read2_b32 v[28:29], v40 offset0:49 offset1:57
	ds_read2_b32 v[30:31], v40 offset0:16 offset1:24
	ds_read2_b32 v[32:33], v40 offset0:82 offset1:90
	ds_read2_b32 v[34:35], v40 offset0:115 offset1:123
	ds_read2_b32 v[36:37], v40 offset0:148 offset1:156
	ds_read2_b32 v[38:39], v40 offset0:181 offset1:189
	ds_read2_b32 v[58:59], v40 offset0:214 offset1:222
	ds_read2_b32 v[62:63], v40 offset0:247 offset1:255
	v_lshl_add_u64 v[20:21], v[60:61], 0, v[6:7]
	v_or_b32_e32 v6, v22, v42
	v_lshlrev_b32_e32 v6, 10, v6
	global_store_dwordx4 v[20:21], v[24:27], off
	v_lshl_add_u64 v[20:21], v[60:61], 0, v[6:7]
	v_or_b32_e32 v6, v22, v43
	s_waitcnt lgkmcnt(6)
	v_cvt_pk_bf16_f32 v24, v30, v28
	s_waitcnt lgkmcnt(4)
	v_cvt_pk_bf16_f32 v25, v32, v34
	s_waitcnt lgkmcnt(2)
	v_cvt_pk_bf16_f32 v26, v36, v38
	s_waitcnt lgkmcnt(0)
	v_cvt_pk_bf16_f32 v27, v58, v62
	v_lshlrev_b32_e32 v6, 10, v6
	global_store_dwordx4 v[20:21], v[24:27], off
	v_lshl_add_u64 v[20:21], v[60:61], 0, v[6:7]
	v_readlane_b32 s94, v250, 3
	v_cvt_pk_bf16_f32 v24, v31, v29
	v_cvt_pk_bf16_f32 v25, v33, v35
	v_cvt_pk_bf16_f32 v26, v37, v39
	v_cvt_pk_bf16_f32 v27, v59, v63
	global_store_dwordx4 v[20:21], v[24:27], off
	s_waitcnt lgkmcnt(0)
	v_readlane_b32 s95, v250, 4

; #define LAS __attribute__((address_space(3)))
; DI unsigned pk2(float lo, float hi) { f32x2 v = {lo, hi}; bf16v2 b = __builtin_convertvector(v, bf16v2); return __builtin_bit_cast(unsigned, b); }
; template <int MODE>
; DI void conv_item(const float* src, const float* src2, const float* rs, bf16_t* dst, int K, int Nsrc, int nblk, LAS float* scr, int item, int lane) {
;     ...
;   const float* sp = s + (long)(k0 + (lane >> 5)) * Nsrc + col;
; #pragma unroll 8
;   for (int i = 0; i < 32; ++i) {
;     const int kk = 2 * i + (lane >> 5);
;     float w = sp[(long)(2 * i) * Nsrc] * cs;
;     if (rs) w *= rs[k0 + kk];
;     scr[kk * 33 + (lane & 31)] = w;
;   }
;   asm volatile("s_waitcnt lgkmcnt(0)" ::: "memory");
;   const int c = lane & 7;
; #pragma unroll
;   for (int j = 0; j < 4; ++j) {
;     const int nn = (lane >> 3) + 8 * j; const LAS float* q = scr + (8 * c) * 33 + nn;
;     u32x4 o; o.x = pk2(q[0], q[33]); o.y = pk2(q[2 * 33], q[3 * 33]); o.z = pk2(q[4 * 33], q[5 * 33]); o.w = pk2(q[6 * 33], q[7 * 33]);
;     *(u32x4*)(dst + (long)(n0 + nn) * K + k0 + 8 * c) = o;
;   }
.LBB0_69:
	s_lshl_b32 s20, s65, 11
	s_add_i32 s69, s65, 2
	s_add_i32 s82, s65, 4
	v_lshl_add_u64 v[24:25], s[20:21], 2, v[20:21]
	s_lshl_b32 s20, s69, 11
	s_lshl_b32 s56, s64, 11
	s_mov_b32 s57, s21
	s_add_i32 s84, s65, 6
	v_lshl_add_u64 v[28:29], s[20:21], 2, v[20:21]
	s_lshl_b32 s20, s82, 11
	s_add_i32 s73, s64, 2
	s_add_i32 s83, s64, 4
	s_add_i32 s85, s64, 6
	s_add_i32 s86, s65, 8
	s_add_i32 s87, s64, 8
	s_add_i32 s89, s64, 10
	s_add_i32 s91, s64, 12
	s_add_i32 s93, s64, 14
	v_lshl_add_u64 v[26:27], s[56:57], 2, v[20:21]
	global_load_dword v6, v[24:25], off nt
	global_load_dword v57, v[26:27], off nt
	v_lshl_add_u64 v[24:25], s[20:21], 2, v[20:21]
	s_lshl_b32 s20, s84, 11
	s_mov_b32 s59, s21
	s_mov_b32 s61, s21
	s_mov_b32 s63, s21
	s_mov_b32 s75, s21
	s_add_i32 s88, s65, 10
	s_mov_b32 s77, s21
	s_mov_b32 s79, s21
	s_mov_b32 s81, s21
	s_lshl_b32 s58, s73, 11
	s_lshl_b32 s60, s83, 11
	s_lshl_b32 s62, s85, 11
	s_lshl_b32 s74, s87, 11
	s_lshl_b32 s76, s89, 11
	s_lshl_b32 s78, s91, 11
	s_lshl_b32 s80, s93, 11
	v_lshl_add_u64 v[26:27], s[20:21], 2, v[20:21]
	s_lshl_b32 s20, s86, 11
	s_add_i32 s90, s65, 12
	v_lshl_add_u64 v[30:31], s[58:59], 2, v[20:21]
	v_lshl_add_u64 v[32:33], s[60:61], 2, v[20:21]
	v_lshl_add_u64 v[34:35], s[62:63], 2, v[20:21]
	v_lshl_add_u64 v[36:37], s[74:75], 2, v[20:21]
	v_lshl_add_u64 v[38:39], s[76:77], 2, v[20:21]
	v_lshl_add_u64 v[58:59], s[78:79], 2, v[20:21]
	v_lshl_add_u64 v[60:61], s[80:81], 2, v[20:21]
	global_load_dword v74, v[28:29], off nt
	global_load_dword v75, v[30:31], off nt
	global_load_dword v76, v[32:33], off nt
	global_load_dword v77, v[34:35], off nt
	global_load_dword v78, v[36:37], off nt
	global_load_dword v79, v[38:39], off nt
	global_load_dword v80, v[58:59], off nt
	global_load_dword v81, v[60:61], off nt
	global_load_dword v82, v[26:27], off nt
	global_load_dword v83, v[24:25], off nt
	v_lshl_add_u64 v[24:25], s[20:21], 2, v[20:21]
	s_lshl_b32 s20, s88, 11
	s_add_i32 s92, s65, 14
	v_lshl_add_u64 v[26:27], s[20:21], 2, v[20:21]
	s_lshl_b32 s20, s90, 11
	v_lshl_add_u64 v[28:29], s[20:21], 2, v[20:21]
	s_lshl_b32 s20, s92, 11
	v_lshl_add_u64 v[30:31], s[20:21], 2, v[20:21]
	global_load_dword v84, v[30:31], off nt
	global_load_dword v85, v[28:29], off nt
	global_load_dword v86, v[26:27], off nt
	global_load_dword v87, v[24:25], off nt
	s_lshl_b32 s67, s64, 1
	s_lshl_b32 s68, s65, 1
	v_or_b32_e32 v26, s67, v1
	v_or_b32_e32 v24, s68, v2
	s_add_i32 s65, s65, 16
	s_add_i32 s64, s64, 16
	s_add_i32 s66, s66, -16
	s_lshl_b32 s20, s73, 1
	s_lshl_b32 s58, s69, 1
	s_lshl_b32 s59, s83, 1
	s_lshl_b32 s60, s82, 1
	s_lshl_b32 s61, s85, 1
	s_lshl_b32 s62, s84, 1
	s_lshl_b32 s63, s87, 1
	s_lshl_b32 s67, s86, 1
	s_lshl_b32 s68, s89, 1
	s_lshl_b32 s69, s88, 1
	s_lshl_b32 s73, s91, 1
	s_lshl_b32 s74, s90, 1
	s_lshl_b32 s75, s93, 1
	s_lshl_b32 s76, s92, 1
	v_mad_u64_u32 v[24:25], s[56:57], v24, s18, v[4:5]
	v_mad_u64_u32 v[26:27], s[56:57], v26, s18, v[4:5]
	v_or_b32_e32 v25, s20, v1
	v_or_b32_e32 v27, s58, v2
	v_or_b32_e32 v34, s59, v1
	v_or_b32_e32 v32, s60, v2
	v_or_b32_e32 v38, s61, v1
	v_or_b32_e32 v36, s62, v2
	v_or_b32_e32 v60, s63, v1
	v_or_b32_e32 v58, s67, v2
	v_or_b32_e32 v64, s68, v1
	v_or_b32_e32 v62, s69, v2
	v_or_b32_e32 v68, s73, v1
	v_or_b32_e32 v66, s74, v2
	v_or_b32_e32 v72, s75, v1
	v_or_b32_e32 v70, s76, v2
	s_cmp_lg_u32 s66, 0
	v_mad_u64_u32 v[28:29], s[56:57], v27, s18, v[4:5]
	v_mad_u64_u32 v[30:31], s[56:57], v25, s18, v[4:5]
	v_mad_u64_u32 v[32:33], s[56:57], v32, s18, v[4:5]
	v_mad_u64_u32 v[34:35], s[56:57], v34, s18, v[4:5]
	v_mad_u64_u32 v[36:37], s[56:57], v36, s18, v[4:5]
	v_mad_u64_u32 v[38:39], s[56:57], v38, s18, v[4:5]
	v_mad_u64_u32 v[58:59], s[56:57], v58, s18, v[4:5]
	v_mad_u64_u32 v[60:61], s[56:57], v60, s18, v[4:5]
	v_mad_u64_u32 v[62:63], s[56:57], v62, s18, v[4:5]
	v_mad_u64_u32 v[64:65], s[56:57], v64, s18, v[4:5]
	v_mad_u64_u32 v[66:67], s[56:57], v66, s18, v[4:5]
	v_mad_u64_u32 v[68:69], s[56:57], v68, s18, v[4:5]
	v_mad_u64_u32 v[70:71], s[56:57], v70, s18, v[4:5]
	v_mad_u64_u32 v[72:73], s[56:57], v72, s18, v[4:5]
	s_waitcnt vmcnt(15)
	ds_write_b32 v24, v6
	s_waitcnt vmcnt(14)
	ds_write_b32 v26, v57
	s_waitcnt vmcnt(13)
	ds_write_b32 v28, v74
	s_waitcnt vmcnt(12)
	ds_write_b32 v30, v75
	s_waitcnt vmcnt(4)
	ds_write_b32 v32, v83
	ds_write_b32 v34, v76
	ds_write_b32 v36, v82
	ds_write_b32 v38, v77
	s_waitcnt vmcnt(0)
	ds_write_b32 v58, v87
	ds_write_b32 v60, v78
	ds_write_b32 v62, v86
	ds_write_b32 v64, v79
	ds_write_b32 v66, v85
	ds_write_b32 v68, v80
	ds_write_b32 v70, v84
	ds_write_b32 v72, v81
	s_cbranch_scc1 .LBB0_69
	s_waitcnt lgkmcnt(0)
	ds_read2_b32 v[20:21], v40 offset0:33 offset1:41
	ds_read2_b32 v[28:29], v40 offset1:8
	ds_read2_b32 v[30:31], v40 offset0:66 offset1:74
	ds_read2_b32 v[32:33], v40 offset0:99 offset1:107
	ds_read2_b32 v[34:35], v40 offset0:132 offset1:140
	ds_read2_b32 v[36:37], v40 offset0:165 offset1:173
	ds_read2_b32 v[38:39], v40 offset0:198 offset1:206
	ds_read2_b32 v[58:59], v40 offset0:231 offset1:239
	v_lshlrev_b32_e32 v6, 1, v23
	v_lshl_add_u64 v[60:61], v[18:19], 0, v[6:7]
	v_or_b32_e32 v6, v22, v5
	v_lshlrev_b32_e32 v6, 11, v6
	s_waitcnt lgkmcnt(6)
	v_cvt_pk_bf16_f32 v24, v28, v20
	s_waitcnt lgkmcnt(4)
	v_cvt_pk_bf16_f32 v25, v30, v32
	s_waitcnt lgkmcnt(2)
	v_cvt_pk_bf16_f32 v26, v34, v36
	s_waitcnt lgkmcnt(0)
	v_cvt_pk_bf16_f32 v27, v38, v58
	v_lshl_add_u64 v[62:63], v[60:61], 0, v[6:7]
	global_store_dwordx4 v[62:63], v[24:27], off
	v_or_b32_e32 v6, v22, v41
	v_lshlrev_b32_e32 v6, 11, v6
	v_cvt_pk_bf16_f32 v24, v29, v21
	v_cvt_pk_bf16_f32 v25, v31, v33
	v_cvt_pk_bf16_f32 v26, v35, v37
	v_cvt_pk_bf16_f32 v27, v39, v59
	ds_read2_b32 v[28:29], v40 offset0:49 offset1:57
	ds_read2_b32 v[30:31], v40 offset0:16 offset1:24
	ds_read2_b32 v[32:33], v40 offset0:82 offset1:90
	ds_read2_b32 v[34:35], v40 offset0:115 offset1:123
	ds_read2_b32 v[36:37], v40 offset0:148 offset1:156
	ds_read2_b32 v[38:39], v40 offset0:181 offset1:189
	ds_read2_b32 v[58:59], v40 offset0:214 offset1:222
	ds_read2_b32 v[62:63], v40 offset0:247 offset1:255
	v_lshl_add_u64 v[20:21], v[60:61], 0, v[6:7]
	v_or_b32_e32 v6, v22, v42
	v_lshlrev_b32_e32 v6, 11, v6
	global_store_dwordx4 v[20:21], v[24:27], off
	v_lshl_add_u64 v[20:21], v[60:61], 0, v[6:7]
	v_or_b32_e32 v6, v22, v43
	s_waitcnt lgkmcnt(6)
	v_cvt_pk_bf16_f32 v24, v30, v28
	s_waitcnt lgkmcnt(4)
	v_cvt_pk_bf16_f32 v25, v32, v34
	s_waitcnt lgkmcnt(2)
	v_cvt_pk_bf16_f32 v26, v36, v38
	s_waitcnt lgkmcnt(0)
	v_cvt_pk_bf16_f32 v27, v58, v62
	v_lshlrev_b32_e32 v6, 11, v6
	global_store_dwordx4 v[20:21], v[24:27], off
	v_lshl_add_u64 v[20:21], v[60:61], 0, v[6:7]
	s_nop 0
	v_cvt_pk_bf16_f32 v24, v31, v29
	v_cvt_pk_bf16_f32 v25, v33, v35
	v_cvt_pk_bf16_f32 v26, v37, v39
	v_cvt_pk_bf16_f32 v27, v59, v63
	global_store_dwordx4 v[20:21], v[24:27], off
	s_waitcnt lgkmcnt(0)

; template <int MODE>
; DI void conv_item(const float* src, const float* src2, const float* rs, bf16_t* dst, int K, int Nsrc, int nblk, LAS float* scr, int item, int lane) {
;     ...
;   const int n = n0 + (lane & 31);
;   int col = n; float cs = 1.f; const float* s = src;
;   if (MODE == 0) {
;     if (n < 1024) { const int head = n >> 7, pp = n & 127, half = (pp >> 4) & 1, jj = pp >> 5, i = pp & 15; col = head * 128 + half * 64 + jj * 16 + i; if (n >= 512) cs = 0.08838834764831845f; }
;     else if (n >= 3072 && n < 4096) { const int c = (n - 3072) & 255, base = n - c; col = base + 64 * ((c >> 5) & 3) + 32 * (c >> 7) + 8 * ((c & 15) >> 2) + 4 * ((c >> 4) & 1) + (c & 3); }
;     else if ((n >= 2048 && n < 3072) || n >= 4608) { const int rho = n & 31; col = (n & ~31) + 8 * ((rho & 15) >> 2) + 4 * (rho >> 4) + (rho & 3); }
;   } else if (MODE == 3) {
;     const int rho = n & 31; col = (n & ~31) + 8 * ((rho & 15) >> 2) + 4 * (rho >> 4) + (rho & 3);
;   } else if (MODE == 1) {
;     const int c = n & 255, r7 = c & 127, rho = r7 & 31; col = (n >> 8) * 128 + (r7 & ~31) + 8 * ((rho & 15) >> 2) + 4 * (rho >> 4) + (rho & 3); if (c >> 7) s = src2;
;   }
;   const float* sp = s + (long)(k0 + (lane >> 5)) * Nsrc + col;
; #pragma unroll 8
;   for (int i = 0; i < 32; ++i) {
;     const int kk = 2 * i + (lane >> 5);
;     float w = sp[(long)(2 * i) * Nsrc] * cs;
;     if (rs) w *= rs[k0 + kk];
;     scr[kk * 33 + (lane & 31)] = w;
;   }
.LBB0_79:
	s_or_saveexec_b64 s[0:1], s[4:5]
	v_mov_b32_e32 v21, 1.0
	s_xor_b64 exec, exec, s[0:1]
	v_lshlrev_b32_e32 v22, 4, v22
	v_and_b32_e32 v21, 0xffffff80, v6
	v_and_b32_e32 v22, 48, v22
	v_cmp_lt_i32_e32 vcc, s70, v23
	v_or3_b32 v36, v46, v21, v22
	s_nop 0
	v_cndmask_b32_e32 v21, 1.0, v56, vcc
	s_or_b64 exec, exec, s[0:1]
	v_lshlrev_b32_e32 v20, 6, v20
	v_ashrrev_i32_e32 v37, 31, v36
	v_or_b32_e32 v22, v48, v20
	v_or_b32_e32 v24, v49, v20
	v_or_b32_e32 v26, v50, v20
	v_or_b32_e32 v28, v51, v20
	v_or_b32_e32 v30, v52, v20
	v_or_b32_e32 v32, v53, v20
	v_or_b32_e32 v34, v54, v20
	v_or_b32_e32 v38, v2, v20
	v_lshlrev_b64 v[36:37], 2, v[36:37]
	v_ashrrev_i32_e32 v23, 31, v22
	v_ashrrev_i32_e32 v25, 31, v24
	v_ashrrev_i32_e32 v27, 31, v26
	v_ashrrev_i32_e32 v29, 31, v28
	v_ashrrev_i32_e32 v31, 31, v30
	v_ashrrev_i32_e32 v33, 31, v32
	v_ashrrev_i32_e32 v35, 31, v34
	v_ashrrev_i32_e32 v39, 31, v38
	v_mad_i64_i32 v[36:37], s[0:1], v38, s71, v[36:37]
	v_lshl_add_u64 v[22:23], v[22:23], 2, s[38:39]
	v_lshl_add_u64 v[24:25], v[24:25], 2, s[38:39]
	v_lshl_add_u64 v[26:27], v[26:27], 2, s[38:39]
	v_lshl_add_u64 v[28:29], v[28:29], 2, s[38:39]
	v_lshl_add_u64 v[30:31], v[30:31], 2, s[38:39]
	v_lshl_add_u64 v[32:33], v[32:33], 2, s[38:39]
	v_lshl_add_u64 v[34:35], v[34:35], 2, s[38:39]
	v_lshl_add_u64 v[36:37], s[40:41], 0, v[36:37]
	v_lshl_add_u64 v[38:39], v[38:39], 2, s[38:39]
	s_mov_b64 s[0:1], 0
	v_mov_b32_e32 v57, v47
	s_andn2_b64 vcc, exec, s[52:53]
	s_cbranch_vccnz .LBB0_83
	v_add_co_u32_e32 v120, vcc, 0xfffcc000, v36
	s_nop 1
	v_addc_co_u32_e32 v121, vcc, -1, v37, vcc
	s_mov_b64 s[4:5], 0xd000
	global_load_dword v88, v[120:121], off nt
	v_lshl_add_u64 v[120:121], v[120:121], 0, s[4:5]
	global_load_dword v89, v[120:121], off nt
	v_lshl_add_u64 v[120:121], v[120:121], 0, s[4:5]
	global_load_dword v90, v[120:121], off nt
	v_lshl_add_u64 v[120:121], v[120:121], 0, s[4:5]
	global_load_dword v91, v[120:121], off nt
	v_lshl_add_u64 v[120:121], v[120:121], 0, s[4:5]
	global_load_dword v92, v[120:121], off nt
	v_lshl_add_u64 v[120:121], v[120:121], 0, s[4:5]
	global_load_dword v93, v[120:121], off nt
	v_lshl_add_u64 v[120:121], v[120:121], 0, s[4:5]
	global_load_dword v94, v[120:121], off nt
	v_lshl_add_u64 v[120:121], v[120:121], 0, s[4:5]
	global_load_dword v95, v[120:121], off nt
	v_lshl_add_u64 v[120:121], v[120:121], 0, s[4:5]
	global_load_dword v96, v[120:121], off nt
	v_lshl_add_u64 v[120:121], v[120:121], 0, s[4:5]
	global_load_dword v97, v[120:121], off nt
	v_lshl_add_u64 v[120:121], v[120:121], 0, s[4:5]
	global_load_dword v98, v[120:121], off nt
	v_lshl_add_u64 v[120:121], v[120:121], 0, s[4:5]
	global_load_dword v99, v[120:121], off nt
	v_lshl_add_u64 v[120:121], v[120:121], 0, s[4:5]
	global_load_dword v100, v[120:121], off nt
	v_lshl_add_u64 v[120:121], v[120:121], 0, s[4:5]
	global_load_dword v101, v[120:121], off nt
	v_lshl_add_u64 v[120:121], v[120:121], 0, s[4:5]
	global_load_dword v102, v[120:121], off nt
	v_lshl_add_u64 v[120:121], v[120:121], 0, s[4:5]
	global_load_dword v103, v[120:121], off nt
	v_lshl_add_u64 v[120:121], v[120:121], 0, s[4:5]
	global_load_dword v104, v[38:39], off nt
	global_load_dword v105, v[38:39], off offset:8 nt
	global_load_dword v106, v[38:39], off offset:16 nt
	global_load_dword v107, v[38:39], off offset:24 nt
	global_load_dword v108, v[38:39], off offset:32 nt
	global_load_dword v109, v[38:39], off offset:40 nt
	global_load_dword v110, v[38:39], off offset:48 nt
	global_load_dword v111, v[38:39], off offset:56 nt
	global_load_dword v112, v[38:39], off offset:64 nt
	global_load_dword v113, v[38:39], off offset:72 nt
	global_load_dword v114, v[38:39], off offset:80 nt
	global_load_dword v115, v[38:39], off offset:88 nt
	global_load_dword v116, v[38:39], off offset:96 nt
	global_load_dword v117, v[38:39], off offset:104 nt
	global_load_dword v118, v[38:39], off offset:112 nt
	global_load_dword v119, v[38:39], off offset:120 nt
	s_waitcnt vmcnt(15)
	v_mul_f32_e32 v88, v21, v88
	v_mul_f32_e32 v88, v88, v104
	ds_write_b32 v57, v88
	s_waitcnt vmcnt(14)
	v_mul_f32_e32 v89, v21, v89
	v_mul_f32_e32 v89, v89, v105
	ds_write_b32 v57, v89 offset:264
	s_waitcnt vmcnt(13)
	v_mul_f32_e32 v90, v21, v90
	v_mul_f32_e32 v90, v90, v106
	ds_write_b32 v57, v90 offset:528
	s_waitcnt vmcnt(12)
	v_mul_f32_e32 v91, v21, v91
	v_mul_f32_e32 v91, v91, v107
	ds_write_b32 v57, v91 offset:792
	s_waitcnt vmcnt(11)
	v_mul_f32_e32 v92, v21, v92
	v_mul_f32_e32 v92, v92, v108
	ds_write_b32 v57, v92 offset:1056
	s_waitcnt vmcnt(10)
	v_mul_f32_e32 v93, v21, v93
	v_mul_f32_e32 v93, v93, v109
	ds_write_b32 v57, v93 offset:1320
	s_waitcnt vmcnt(9)
	v_mul_f32_e32 v94, v21, v94
	v_mul_f32_e32 v94, v94, v110
	ds_write_b32 v57, v94 offset:1584
	s_waitcnt vmcnt(8)
	v_mul_f32_e32 v95, v21, v95
	v_mul_f32_e32 v95, v95, v111
	ds_write_b32 v57, v95 offset:1848
	s_waitcnt vmcnt(7)
	v_mul_f32_e32 v96, v21, v96
	v_mul_f32_e32 v96, v96, v112
	ds_write_b32 v57, v96 offset:2112
	s_waitcnt vmcnt(6)
; template <int MODE>
; DI void conv_item(const float* src, const float* src2, const float* rs, bf16_t* dst, int K, int Nsrc, int nblk, LAS float* scr, int item, int lane) {
;     ...
; #pragma unroll 8
;   for (int i = 0; i < 32; ++i) {
;     const int kk = 2 * i + (lane >> 5);
;     float w = sp[(long)(2 * i) * Nsrc] * cs;
;     if (rs) w *= rs[k0 + kk];
;     scr[kk * 33 + (lane & 31)] = w;
;   }
	v_mul_f32_e32 v97, v21, v97
	v_mul_f32_e32 v97, v97, v113
	ds_write_b32 v57, v97 offset:2376
	s_waitcnt vmcnt(5)
	v_mul_f32_e32 v98, v21, v98
	v_mul_f32_e32 v98, v98, v114
	ds_write_b32 v57, v98 offset:2640
	s_waitcnt vmcnt(4)
	v_mul_f32_e32 v99, v21, v99
	v_mul_f32_e32 v99, v99, v115
	ds_write_b32 v57, v99 offset:2904
	s_waitcnt vmcnt(3)
	v_mul_f32_e32 v100, v21, v100
	v_mul_f32_e32 v100, v100, v116
	ds_write_b32 v57, v100 offset:3168
	s_waitcnt vmcnt(2)
	v_mul_f32_e32 v101, v21, v101
	v_mul_f32_e32 v101, v101, v117
	ds_write_b32 v57, v101 offset:3432
	s_waitcnt vmcnt(1)
	v_mul_f32_e32 v102, v21, v102
	v_mul_f32_e32 v102, v102, v118
	ds_write_b32 v57, v102 offset:3696
	s_waitcnt vmcnt(0)
	v_mul_f32_e32 v103, v21, v103
	v_mul_f32_e32 v103, v103, v119
	ds_write_b32 v57, v103 offset:3960
	global_load_dword v88, v[120:121], off nt
	v_lshl_add_u64 v[120:121], v[120:121], 0, s[4:5]
	global_load_dword v89, v[120:121], off nt
	v_lshl_add_u64 v[120:121], v[120:121], 0, s[4:5]
	global_load_dword v90, v[120:121], off nt
	v_lshl_add_u64 v[120:121], v[120:121], 0, s[4:5]
	global_load_dword v91, v[120:121], off nt
	v_lshl_add_u64 v[120:121], v[120:121], 0, s[4:5]
	global_load_dword v92, v[120:121], off nt
	v_lshl_add_u64 v[120:121], v[120:121], 0, s[4:5]
	global_load_dword v93, v[120:121], off nt
	v_lshl_add_u64 v[120:121], v[120:121], 0, s[4:5]
	global_load_dword v94, v[120:121], off nt
	v_lshl_add_u64 v[120:121], v[120:121], 0, s[4:5]
	global_load_dword v95, v[120:121], off nt
	v_lshl_add_u64 v[120:121], v[120:121], 0, s[4:5]
	global_load_dword v96, v[120:121], off nt
	v_lshl_add_u64 v[120:121], v[120:121], 0, s[4:5]
	global_load_dword v97, v[120:121], off nt
	v_lshl_add_u64 v[120:121], v[120:121], 0, s[4:5]
	global_load_dword v98, v[120:121], off nt
	v_lshl_add_u64 v[120:121], v[120:121], 0, s[4:5]
	global_load_dword v99, v[120:121], off nt
	v_lshl_add_u64 v[120:121], v[120:121], 0, s[4:5]
	global_load_dword v100, v[120:121], off nt
	v_lshl_add_u64 v[120:121], v[120:121], 0, s[4:5]
	global_load_dword v101, v[120:121], off nt
	v_lshl_add_u64 v[120:121], v[120:121], 0, s[4:5]
	global_load_dword v102, v[120:121], off nt
	v_lshl_add_u64 v[120:121], v[120:121], 0, s[4:5]
	global_load_dword v103, v[120:121], off nt
	v_lshl_add_u64 v[120:121], v[120:121], 0, s[4:5]
	global_load_dword v104, v[38:39], off offset:128 nt
	global_load_dword v105, v[38:39], off offset:136 nt
	global_load_dword v106, v[38:39], off offset:144 nt
	global_load_dword v107, v[38:39], off offset:152 nt
	global_load_dword v108, v[38:39], off offset:160 nt
	global_load_dword v109, v[38:39], off offset:168 nt
	global_load_dword v110, v[38:39], off offset:176 nt
	global_load_dword v111, v[38:39], off offset:184 nt
	global_load_dword v112, v[38:39], off offset:192 nt
	global_load_dword v113, v[38:39], off offset:200 nt
	global_load_dword v114, v[38:39], off offset:208 nt
	global_load_dword v115, v[38:39], off offset:216 nt
	global_load_dword v116, v[38:39], off offset:224 nt
	global_load_dword v117, v[38:39], off offset:232 nt
	global_load_dword v118, v[38:39], off offset:240 nt
	global_load_dword v119, v[38:39], off offset:248 nt
	s_waitcnt vmcnt(15)
	v_mul_f32_e32 v88, v21, v88
	v_mul_f32_e32 v88, v88, v104
	ds_write_b32 v57, v88 offset:4224
	s_waitcnt vmcnt(14)
	v_mul_f32_e32 v89, v21, v89
	v_mul_f32_e32 v89, v89, v105
	ds_write_b32 v57, v89 offset:4488
	s_waitcnt vmcnt(13)
	v_mul_f32_e32 v90, v21, v90
	v_mul_f32_e32 v90, v90, v106
	ds_write_b32 v57, v90 offset:4752
	s_waitcnt vmcnt(12)
	v_mul_f32_e32 v91, v21, v91
	v_mul_f32_e32 v91, v91, v107
	ds_write_b32 v57, v91 offset:5016
	s_waitcnt vmcnt(11)
	v_mul_f32_e32 v92, v21, v92
	v_mul_f32_e32 v92, v92, v108
	ds_write_b32 v57, v92 offset:5280
	s_waitcnt vmcnt(10)
	v_mul_f32_e32 v93, v21, v93
	v_mul_f32_e32 v93, v93, v109
	ds_write_b32 v57, v93 offset:5544
	s_waitcnt vmcnt(9)
	v_mul_f32_e32 v94, v21, v94
	v_mul_f32_e32 v94, v94, v110
	ds_write_b32 v57, v94 offset:5808
	s_waitcnt vmcnt(8)
	v_mul_f32_e32 v95, v21, v95
	v_mul_f32_e32 v95, v95, v111
	ds_write_b32 v57, v95 offset:6072
	s_waitcnt vmcnt(7)
	v_mul_f32_e32 v96, v21, v96
	v_mul_f32_e32 v96, v96, v112
	ds_write_b32 v57, v96 offset:6336
	s_waitcnt vmcnt(6)
	v_mul_f32_e32 v97, v21, v97
	v_mul_f32_e32 v97, v97, v113
	ds_write_b32 v57, v97 offset:6600
	s_waitcnt vmcnt(5)
	v_mul_f32_e32 v98, v21, v98
	v_mul_f32_e32 v98, v98, v114
	ds_write_b32 v57, v98 offset:6864
	s_waitcnt vmcnt(4)
	v_mul_f32_e32 v99, v21, v99
	v_mul_f32_e32 v99, v99, v115
	ds_write_b32 v57, v99 offset:7128
	s_waitcnt vmcnt(3)
	v_mul_f32_e32 v100, v21, v100
	v_mul_f32_e32 v100, v100, v116
	ds_write_b32 v57, v100 offset:7392
	s_waitcnt vmcnt(2)
	v_mul_f32_e32 v101, v21, v101
	v_mul_f32_e32 v101, v101, v117
	ds_write_b32 v57, v101 offset:7656
	s_waitcnt vmcnt(1)
	v_mul_f32_e32 v102, v21, v102
	v_mul_f32_e32 v102, v102, v118
	ds_write_b32 v57, v102 offset:7920
	s_waitcnt vmcnt(0)
	v_mul_f32_e32 v103, v21, v103
	v_mul_f32_e32 v103, v103, v119
	ds_write_b32 v57, v103 offset:8184
	s_branch .LBB0_26

; template <int MODE>
; DI void conv_item(const float* src, const float* src2, const float* rs, bf16_t* dst, int K, int Nsrc, int nblk, LAS float* scr, int item, int lane) {
;     ...
; #pragma unroll 8
;   for (int i = 0; i < 32; ++i) {
;     const int kk = 2 * i + (lane >> 5);
;     float w = sp[(long)(2 * i) * Nsrc] * cs;
;     if (rs) w *= rs[k0 + kk];
;     scr[kk * 33 + (lane & 31)] = w;
;   }
.LBB0_83:
	v_add_co_u32_e32 v58, vcc, 0xfffcc000, v36
	s_nop 1
	v_addc_co_u32_e32 v59, vcc, -1, v37, vcc
	global_load_dword v58, v[58:59], off nt
	v_cndmask_b32_e64 v59, 0, 1, s[52:53]
	v_cmp_ne_u32_e64 s[4:5], 1, v59
	s_andn2_b64 vcc, exec, s[52:53]
	s_waitcnt vmcnt(0)
	v_mul_f32_e32 v58, v21, v58
	s_cbranch_vccnz .LBB0_85
	v_lshl_add_u64 v[60:61], v[38:39], 0, s[0:1]
	global_load_dword v59, v[60:61], off nt
	s_waitcnt vmcnt(0)
	v_mul_f32_e32 v58, v58, v59
.LBB0_85:
	v_add_co_u32_e32 v60, vcc, 0xfffd9000, v36
	ds_write_b32 v57, v58
	s_nop 0
	v_addc_co_u32_e32 v61, vcc, -1, v37, vcc
	global_load_dword v59, v[60:61], off nt
	s_and_b64 vcc, exec, s[4:5]
	s_waitcnt vmcnt(0)
	v_mul_f32_e32 v58, v21, v59
	s_cbranch_vccnz .LBB0_87
	v_lshl_add_u64 v[60:61], v[34:35], 0, s[0:1]
	global_load_dword v59, v[60:61], off nt
	s_waitcnt vmcnt(0)
	v_mul_f32_e32 v58, v58, v59
.LBB0_87:
	v_add_co_u32_e32 v60, vcc, 0xfffe6000, v36
	ds_write_b32 v57, v58 offset:264
	s_nop 0
	v_addc_co_u32_e32 v61, vcc, -1, v37, vcc
	global_load_dword v59, v[60:61], off nt
	s_and_b64 vcc, exec, s[4:5]
	s_waitcnt vmcnt(0)
	v_mul_f32_e32 v58, v21, v59
	s_cbranch_vccnz .LBB0_89
	v_lshl_add_u64 v[60:61], v[32:33], 0, s[0:1]
	global_load_dword v59, v[60:61], off nt
	s_waitcnt vmcnt(0)
	v_mul_f32_e32 v58, v58, v59
.LBB0_89:
	v_add_co_u32_e32 v60, vcc, 0xffff3000, v36
	ds_write_b32 v57, v58 offset:528
	s_nop 0
	v_addc_co_u32_e32 v61, vcc, -1, v37, vcc
	global_load_dword v59, v[60:61], off nt
	s_and_b64 vcc, exec, s[4:5]
	s_waitcnt vmcnt(0)
	v_mul_f32_e32 v58, v21, v59
	s_cbranch_vccnz .LBB0_91
	v_lshl_add_u64 v[60:61], v[30:31], 0, s[0:1]
	global_load_dword v59, v[60:61], off nt
	s_waitcnt vmcnt(0)
	v_mul_f32_e32 v58, v58, v59
.LBB0_91:
	global_load_dword v59, v[36:37], off nt
	ds_write_b32 v57, v58 offset:792
	s_and_b64 vcc, exec, s[4:5]
	s_waitcnt vmcnt(0)
	v_mul_f32_e32 v58, v21, v59
	s_cbranch_vccnz .LBB0_93
	v_lshl_add_u64 v[60:61], v[28:29], 0, s[0:1]
	global_load_dword v59, v[60:61], off nt
	s_waitcnt vmcnt(0)
	v_mul_f32_e32 v58, v58, v59
.LBB0_93:
	v_add_co_u32_e32 v60, vcc, 0xd000, v36
	ds_write_b32 v57, v58 offset:1056
	s_nop 0
	v_addc_co_u32_e32 v61, vcc, 0, v37, vcc
	global_load_dword v59, v[60:61], off nt
	s_and_b64 vcc, exec, s[4:5]
	s_waitcnt vmcnt(0)
	v_mul_f32_e32 v58, v21, v59
	s_cbranch_vccnz .LBB0_95
	v_lshl_add_u64 v[60:61], v[26:27], 0, s[0:1]
	global_load_dword v59, v[60:61], off nt
	s_waitcnt vmcnt(0)
	v_mul_f32_e32 v58, v58, v59
.LBB0_95:
	v_add_co_u32_e32 v60, vcc, 0x1a000, v36
	ds_write_b32 v57, v58 offset:1320
	s_nop 0
	v_addc_co_u32_e32 v61, vcc, 0, v37, vcc
	global_load_dword v59, v[60:61], off nt
	s_and_b64 vcc, exec, s[4:5]
	s_waitcnt vmcnt(0)
	v_mul_f32_e32 v58, v21, v59
	s_cbranch_vccnz .LBB0_97
	v_lshl_add_u64 v[60:61], v[24:25], 0, s[0:1]
	global_load_dword v59, v[60:61], off nt
	s_waitcnt vmcnt(0)
	v_mul_f32_e32 v58, v58, v59
.LBB0_97:
	v_add_co_u32_e32 v60, vcc, 0x27000, v36
	ds_write_b32 v57, v58 offset:1584
	s_nop 0
	v_addc_co_u32_e32 v61, vcc, 0, v37, vcc
	global_load_dword v59, v[60:61], off nt
	s_and_b64 vcc, exec, s[4:5]
	s_waitcnt vmcnt(0)
	v_mul_f32_e32 v58, v21, v59
	s_cbranch_vccnz .LBB0_82
	v_lshl_add_u64 v[60:61], v[22:23], 0, s[0:1]
	global_load_dword v59, v[60:61], off nt
	s_waitcnt vmcnt(0)
	v_mul_f32_e32 v58, v58, v59
	s_branch .LBB0_82

;     ...
;   if (blockIdx.x == 0 && threadIdx.x < 64) {
;     float a = fabsf(p.q_norm_w[threadIdx.x]), b = fabsf(p.k_norm_w[threadIdx.x]);
; #pragma unroll
;     for (int o = 1; o < 64; o <<= 1) { a = fmaxf(a, __shfl_xor(a, o)); b = fmaxf(b, __shfl_xor(b, o)); }
;     if (threadIdx.x == 0) ((float*)(ws + OFF_SC))[0] = 8.0f * a * b * 1.01f;
;   }
.LBB0_102:
	s_or_b64 exec, exec, s[0:1]
	s_cmp_eq_u32 s2, 0
	s_cselect_b64 s[0:1], -1, 0
	v_cmp_gt_u32_e32 vcc, 64, v194
	s_and_b64 s[4:5], s[0:1], vcc
	s_and_saveexec_b64 s[0:1], s[4:5]
	s_cbranch_execz .LBB0_105
	v_lshlrev_b32_e32 v1, 2, v194
	global_load_dword v2, v1, s[42:43] nt
	global_load_dword v3, v1, s[44:45] nt
	v_mbcnt_lo_u32_b32 v1, -1, 0
	v_mbcnt_hi_u32_b32 v1, -1, v1
	v_and_b32_e32 v4, 64, v1
	v_xor_b32_e32 v5, 1, v1
	v_add_u32_e32 v4, 64, v4
	v_cmp_lt_i32_e32 vcc, v5, v4
	v_xor_b32_e32 v6, 2, v1
	v_xor_b32_e32 v7, 4, v1
	v_cndmask_b32_e32 v5, v1, v5, vcc
	v_lshlrev_b32_e32 v5, 2, v5
	v_cmp_lt_i32_e32 vcc, v6, v4
	v_xor_b32_e32 v8, 8, v1
	v_xor_b32_e32 v9, 16, v1
	v_cndmask_b32_e32 v6, v1, v6, vcc
	v_lshlrev_b32_e32 v6, 2, v6
	v_cmp_lt_i32_e32 vcc, v7, v4
	v_xor_b32_e32 v10, 32, v1
	s_waitcnt vmcnt(1)
	v_and_b32_e32 v11, 0x7fffffff, v2
	s_waitcnt vmcnt(0)
	v_and_b32_e32 v12, 0x7fffffff, v3
	ds_bpermute_b32 v11, v5, v11
	ds_bpermute_b32 v5, v5, v12
	v_max_f32_e64 v2, |v2|, |v2|
	v_max_f32_e64 v3, |v3|, |v3|
	v_cndmask_b32_e32 v7, v1, v7, vcc
	s_waitcnt lgkmcnt(1)
	v_max_f32_e32 v11, v11, v11
	s_waitcnt lgkmcnt(0)
	v_max_f32_e32 v5, v5, v5
	v_max_f32_e32 v2, v2, v11
	v_max_f32_e32 v3, v3, v5
	ds_bpermute_b32 v5, v6, v2
	ds_bpermute_b32 v6, v6, v3
	v_lshlrev_b32_e32 v7, 2, v7
	v_cmp_lt_i32_e32 vcc, v8, v4
	s_waitcnt lgkmcnt(1)
	v_max_f32_e32 v5, v5, v5
	s_waitcnt lgkmcnt(0)
	v_max_f32_e32 v6, v6, v6
	v_max_f32_e32 v2, v2, v5
	v_max_f32_e32 v3, v3, v6
	ds_bpermute_b32 v5, v7, v2
	ds_bpermute_b32 v6, v7, v3
	v_cndmask_b32_e32 v7, v1, v8, vcc
	v_lshlrev_b32_e32 v7, 2, v7
	v_cmp_lt_i32_e32 vcc, v9, v4
	s_waitcnt lgkmcnt(1)
	v_max_f32_e32 v5, v5, v5
	s_waitcnt lgkmcnt(0)
	v_max_f32_e32 v6, v6, v6
	v_max_f32_e32 v2, v2, v5
	v_max_f32_e32 v3, v3, v6
	ds_bpermute_b32 v5, v7, v2
	ds_bpermute_b32 v6, v7, v3
	v_cndmask_b32_e32 v7, v1, v9, vcc
	v_lshlrev_b32_e32 v7, 2, v7
	v_cmp_lt_i32_e32 vcc, v10, v4
	s_waitcnt lgkmcnt(1)
	v_max_f32_e32 v5, v5, v5
	s_waitcnt lgkmcnt(0)
	v_max_f32_e32 v6, v6, v6
	v_max_f32_e32 v2, v2, v5
	v_max_f32_e32 v3, v3, v6
	ds_bpermute_b32 v5, v7, v2
	ds_bpermute_b32 v6, v7, v3
	v_cndmask_b32_e32 v1, v1, v10, vcc
	v_lshlrev_b32_e32 v4, 2, v1
	s_waitcnt lgkmcnt(1)
	v_max_f32_e32 v1, v5, v5
	s_waitcnt lgkmcnt(0)
	v_max_f32_e32 v5, v6, v6
	v_max_f32_e32 v1, v2, v1
	v_max_f32_e32 v3, v3, v5
	ds_bpermute_b32 v2, v4, v1
	ds_bpermute_b32 v4, v4, v3
	s_and_b64 exec, exec, s[94:95]
	s_cbranch_execz .LBB0_105
	s_waitcnt lgkmcnt(1)
	v_max_f32_e32 v2, v2, v2
	v_max_f32_e32 v1, v1, v1
	s_waitcnt lgkmcnt(0)
	v_max_f32_e32 v4, v4, v4
	v_max_f32_e32 v3, v3, v3
	v_max_f32_e32 v1, v1, v2
	v_max_f32_e32 v3, v3, v4
	v_mul_f32_e32 v1, 0x41000000, v1
	v_mul_f32_e32 v1, v1, v3
	v_mul_f32_e32 v1, 0x3f8147ae, v1
	v_mov_b32_e32 v2, 0x1e7e0000
	global_store_dword v2, v1, s[26:27]

; #define LAS __attribute__((address_space(3)))
; #define RO_BARRIER do { asm volatile("s_waitcnt lgkmcnt(0)" ::: "memory"); __builtin_amdgcn_s_barrier(); asm volatile("" ::: "memory"); } while (0)
;     ...
;     {
;       const u32x4* qg = (const u32x4*)(Qr + (long)(bh * 64 + c) * 16384); const u32x4* kg = (const u32x4*)(Kr + (long)(bh * 64 + c) * 16384);
;       u32x4 qv[4], kv[4];
; #pragma unroll
;       for (int i = 0; i < 4; ++i) { qv[i] = qg[tid + i * NTHREADS]; kv[i] = kg[tid + i * NTHREADS]; }
; #pragma unroll
;       for (int i = 0; i < 4; ++i) { *(LAS u32x4*)(shm + RO_Q + (tid + i * NTHREADS) * 16) = qv[i]; *(LAS u32x4*)(shm + RO_K + (tid + i * NTHREADS) * 16) = kv[i]; }
;     }
;     bf16x8 rf[2][4], vf[2][4];
;     {
;       const bf16_t* rp = RT + (long)(bh * 64 + c) * 32768 + (2 * wid) * 2048 + lane * 8;
;       const bf16_t* vp = Vrt + (long)(bh * 64 + c) * 32768 + (2 * wid) * 2048 + lane * 8;
; #pragma unroll
;       for (int e2 = 0; e2 < 2; ++e2)
; #pragma unroll
;         for (int ks = 0; ks < 4; ++ks) { rf[e2][ks] = *(const bf16x8*)(rp + e2 * 2048 + ks * 512); vf[e2][ks] = *(const bf16x8*)(vp + e2 * 2048 + ks * 512); }
;     }
;     RO_BARRIER;
;     {
;       const int ns2 = (16 * wid + 15) / 32 + 1, n = 16 * wid + fr;
;       bf16x8 qb[4];
; #pragma unroll
;       for (int ks = 0; ks < 4; ++ks) qb[ks] = *(const LAS bf16x8*)(shm + RO_Q + (wid * 4 + ks) * 1024 + lane * 16);
.LBB0_734:
	s_ashr_i32 s47, s46, 31
	s_lshl_b64 s[0:1], s[46:47], 15
	v_lshl_add_u64 v[0:1], v[96:97], 0, s[0:1]
	v_add_co_u32_e32 v4, vcc, 0x2000, v0
	v_lshl_add_u64 v[2:3], v[98:99], 0, s[0:1]
	s_nop 0
	v_addc_co_u32_e32 v5, vcc, 0, v1, vcc
	v_add_co_u32_e32 v6, vcc, 0x2000, v2
	global_load_dwordx4 v[32:35], v[0:1], off nt
	global_load_dwordx4 v[36:39], v[2:3], off nt
	v_addc_co_u32_e32 v7, vcc, 0, v3, vcc
	global_load_dwordx4 v[40:43], v[4:5], off nt
	global_load_dwordx4 v[44:47], v[6:7], off nt
	v_add_co_u32_e32 v4, vcc, 0x4000, v0
	s_lshl_b64 s[0:1], s[46:47], 16
	s_nop 0
	v_addc_co_u32_e32 v5, vcc, 0, v1, vcc
	v_add_co_u32_e32 v6, vcc, 0x4000, v2
	s_nop 1
	v_addc_co_u32_e32 v7, vcc, 0, v3, vcc
	v_add_co_u32_e32 v0, vcc, 0x6000, v0
	global_load_dwordx4 v[50:53], v[4:5], off nt
	global_load_dwordx4 v[142:145], v[6:7], off nt
	v_addc_co_u32_e32 v1, vcc, 0, v1, vcc
	v_add_co_u32_e32 v2, vcc, 0x6000, v2
	s_nop 1
	v_addc_co_u32_e32 v3, vcc, 0, v3, vcc
	global_load_dwordx4 v[146:149], v[0:1], off nt
	global_load_dwordx4 v[150:153], v[2:3], off nt
	v_lshl_add_u64 v[0:1], v[92:93], 0, s[0:1]
	v_lshl_add_u64 v[2:3], v[94:95], 0, s[0:1]
	global_load_dwordx4 v[12:15], v[0:1], off nt
	global_load_dwordx4 v[16:19], v[0:1], off offset:1024 nt
	global_load_dwordx4 v[76:79], v[2:3], off nt
	global_load_dwordx4 v[68:71], v[2:3], off offset:1024 nt
	global_load_dwordx4 v[4:7], v[0:1], off offset:2048 nt
	global_load_dwordx4 v[8:11], v[0:1], off offset:3072 nt
	global_load_dwordx4 v[60:63], v[2:3], off offset:2048 nt
	global_load_dwordx4 v[56:59], v[2:3], off offset:3072 nt
	v_add_co_u32_e32 v0, vcc, s43, v0
	s_nop 1
	v_addc_co_u32_e32 v1, vcc, 0, v1, vcc
	v_add_co_u32_e32 v54, vcc, s43, v2
	s_nop 1
	v_addc_co_u32_e32 v55, vcc, 0, v3, vcc
	global_load_dwordx4 v[24:27], v[0:1], off nt
	global_load_dwordx4 v[28:31], v[0:1], off offset:1024 nt
	global_load_dwordx4 v[84:87], v[54:55], off nt
	global_load_dwordx4 v[80:83], v[54:55], off offset:1024 nt
	global_load_dwordx4 v[20:23], v[0:1], off offset:2048 nt
	s_nop 0
	global_load_dwordx4 v[0:3], v[0:1], off offset:3072 nt
	s_nop 0
	global_load_dwordx4 v[72:75], v[54:55], off offset:2048 nt
	global_load_dwordx4 v[64:67], v[54:55], off offset:3072 nt
	s_andn2_b64 vcc, exec, s[40:41]
	s_waitcnt vmcnt(23)
	ds_write_b128 v135, v[32:35]
	s_waitcnt vmcnt(22)
	ds_write_b128 v135, v[36:39] offset:32768
	s_waitcnt vmcnt(21)
	ds_write_b128 v135, v[40:43] offset:8192
	s_waitcnt vmcnt(20)
	ds_write_b128 v135, v[44:47] offset:40960
	s_waitcnt vmcnt(19)
	ds_write_b128 v135, v[50:53] offset:16384
	s_waitcnt vmcnt(18)
	ds_write_b128 v135, v[142:145] offset:49152
	s_waitcnt vmcnt(17)
	ds_write_b128 v135, v[146:149] offset:24576
	s_waitcnt vmcnt(16)
	ds_write_b128 v135, v[150:153] offset:57344
	s_waitcnt lgkmcnt(0)
	s_barrier
	s_cbranch_vccnz .LBB0_737
	v_add_u32_e32 v44, s3, v88
	ds_read_b128 v[32:35], v44
	ds_read_b128 v[36:39], v44 offset:1024
	ds_read_b128 v[40:43], v44 offset:2048
	ds_read_b128 v[44:47], v44 offset:3072
	v_mov_b32_e32 v49, v134
	v_mov_b32_e32 v50, v133
	v_mov_b32_e32 v51, v132
	s_mov_b32 s47, s39
